# conv epilogue + sc1 write-through stores in GEMM/post epilogues + leaner hand-written grid barrier (top counter polled directly, local release before leader acquire)
# speedup vs baseline: 1.0213x; 1.0213x over previous
_Z4mega6Params:
	v_mov_b32_e32 v254, 0
	s_load_dwordx4 s[12:15], s[0:1], 0xf8
	s_load_dwordx2 s[88:89], s[0:1], 0xf0
	s_mov_b32 s90, s2
	v_cmp_eq_u32_e32 vcc, 0, v0
	s_waitcnt lgkmcnt(0)
	s_cmp_lg_u32 s14, 0
	s_cselect_b64 s[2:3], -1, 0
	v_writelane_b32 v252, s2, 0
	s_cmp_eq_u32 s14, 0
	s_nop 0
	v_writelane_b32 v252, s3, 1
	s_cbranch_scc1 .LBB0_7
	s_and_saveexec_b64 s[2:3], vcc
	s_cbranch_execz .LBB0_3
	v_mov_b32_e32 v1, 0
	v_mov_b32_e32 v2, 0x22800
	ds_write_b32 v2, v1
	v_mov_b32_e32 v2, 0x22804
	ds_write_b32 v2, v1

.LBB0_7:
	s_mov_b64 s[4:5], s[12:13]
	v_writelane_b32 v252, s4, 2
	s_cmp_ge_i32 s12, s13
	s_nop 0
	v_writelane_b32 v252, s5, 3
	v_writelane_b32 v252, s6, 4
	v_writelane_b32 v252, s7, 5
	s_cbranch_scc1 .LBB0_1354
	s_load_dwordx4 s[84:87], s[0:1], 0xe0
	s_load_dwordx8 s[4:11], s[0:1], 0xc0
	s_add_u32 s2, s88, 0x10000
	s_addc_u32 s3, s89, 0
	v_mbcnt_lo_u32_b32 v2, -1, 0
	v_mbcnt_hi_u32_b32 v229, -1, v2
	s_waitcnt lgkmcnt(0)
	v_writelane_b32 v252, s4, 6
	v_and_b32_e32 v2, 64, v229
	v_mov_b32_e32 v3, 0
	v_writelane_b32 v252, s5, 7
	v_writelane_b32 v252, s6, 8
	v_writelane_b32 v252, s7, 9
	v_writelane_b32 v252, s8, 10
	v_writelane_b32 v252, s9, 11
	v_writelane_b32 v252, s10, 12
	v_writelane_b32 v252, s11, 13
	s_load_dwordx16 s[4:19], s[0:1], 0x0
	s_movk_i32 s95, 0x2000
	v_mov_b32_e32 v1, 0x358637bd
	s_mov_b32 s91, 0x800000
	s_mov_b64 s[82:83], 0x80
	s_waitcnt lgkmcnt(0)
	v_writelane_b32 v252, s4, 14
	s_mov_b32 s33, 0x3e16c740
	s_mov_b64 s[92:93], 0x200
	v_writelane_b32 v252, s5, 15
	v_writelane_b32 v252, s6, 16
	v_writelane_b32 v252, s7, 17
	v_writelane_b32 v252, s8, 18
	v_writelane_b32 v252, s9, 19
	v_writelane_b32 v252, s10, 20
	v_writelane_b32 v252, s11, 21
	v_writelane_b32 v252, s12, 22
	v_writelane_b32 v252, s13, 23
	v_writelane_b32 v252, s14, 24
	v_writelane_b32 v252, s15, 25
	v_writelane_b32 v252, s16, 26
	v_writelane_b32 v252, s17, 27
	v_writelane_b32 v252, s18, 28
	v_writelane_b32 v252, s19, 29
	s_load_dwordx16 s[4:19], s[0:1], 0x40
	s_mov_b64 s[80:81], 0x1200
	v_mov_b32_e32 v226, 0x22800
	v_mov_b32_e32 v227, 0x22804
	v_mov_b32_e32 v228, 1
	s_waitcnt lgkmcnt(0)
	v_writelane_b32 v252, s4, 30
	v_xor_b32_e32 v230, 16, v229
	v_add_u32_e32 v231, 64, v2
	v_writelane_b32 v252, s5, 31
	v_writelane_b32 v252, s6, 32
	v_writelane_b32 v252, s7, 33
	v_writelane_b32 v252, s8, 34
	v_writelane_b32 v252, s9, 35
	v_writelane_b32 v252, s10, 36
	v_writelane_b32 v252, s11, 37
	v_writelane_b32 v252, s12, 38
	v_writelane_b32 v252, s13, 39
	v_writelane_b32 v252, s14, 40
	v_writelane_b32 v252, s15, 41
	v_writelane_b32 v252, s16, 42
	v_writelane_b32 v252, s17, 43
	v_writelane_b32 v252, s18, 44
	v_writelane_b32 v252, s19, 45
	s_load_dwordx16 s[4:19], s[0:1], 0x80
	v_mov_b64_e32 v[180:181], 0x100
	v_mov_b64_e32 v[182:183], 0xff
	v_mov_b32_e32 v232, 0x1000
	v_mov_b32_e32 v233, 0x100
	s_waitcnt lgkmcnt(0)
	v_writelane_b32 v252, s4, 46
	v_mov_b32_e32 v234, 0x20000
	v_mov_b64_e32 v[184:185], 0x57f
	v_writelane_b32 v252, s5, 47
	v_writelane_b32 v252, s6, 48
	v_writelane_b32 v252, s7, 49
	v_writelane_b32 v252, s8, 50
	v_writelane_b32 v252, s9, 51
	v_writelane_b32 v252, s10, 52
	v_writelane_b32 v252, s11, 53
	v_writelane_b32 v252, s12, 54
	v_writelane_b32 v252, s13, 55
	v_writelane_b32 v252, s14, 56
	v_writelane_b32 v252, s15, 57
	v_writelane_b32 v252, s16, 58
	v_writelane_b32 v252, s17, 59
	v_writelane_b32 v252, s18, 60
	v_writelane_b32 v252, s19, 61
	v_writelane_b32 v252, s2, 62
	v_mov_b64_e32 v[186:187], 0x580
	v_mov_b32_e32 v188, 0x22808
	v_writelane_b32 v252, s3, 63
	s_add_u32 s2, s88, 0x4000
	v_writelane_b32 v253, s2, 0
	s_addc_u32 s2, s89, 0
	s_add_u32 s0, s0, 0x108
	v_writelane_b32 v253, s2, 1
	s_addc_u32 s1, s1, 0
	v_writelane_b32 v253, s0, 2
	v_mov_b32_e32 v235, 0x70
	v_mov_b32_e32 v236, 0x42800000
	v_writelane_b32 v253, s1, 3
	s_lshl_b32 s0, s90, 3
	s_add_u32 s10, s88, 0x6198000
	s_addc_u32 s11, s89, 0
	v_writelane_b32 v253, s0, 4
	s_add_u32 s0, s88, 0x14340000
	s_addc_u32 s1, s89, 0
	v_writelane_b32 v253, s0, 5
	v_not_b32_e32 v237, 63
	v_mov_b32_e32 v238, 0x200
	v_writelane_b32 v253, s1, 6
	s_lshl_b32 s0, s90, 9
	s_cmpk_lt_i32 s90, 0x5cc
	v_writelane_b32 v253, s0, 7
	s_cselect_b64 s[0:1], -1, 0
	v_writelane_b32 v253, s0, 8
	v_mov_b64_e32 v[190:191], 0x23f
	v_mov_b64_e32 v[192:193], 0x240
	v_writelane_b32 v253, s1, 9
	s_add_u32 s0, s88, 0x6118000
	v_writelane_b32 v253, s0, 10
	s_addc_u32 s0, s89, 0
	v_writelane_b32 v253, s0, 11
	s_add_u32 s0, s88, 0x5f18000
	v_writelane_b32 v253, s0, 12
	s_addc_u32 s0, s89, 0
	v_writelane_b32 v253, s0, 13
	s_add_u32 s0, s88, 0x4798000
	s_addc_u32 s1, s89, 0
	v_writelane_b32 v253, s0, 14
	s_nop 1
	v_writelane_b32 v253, s1, 15
	s_add_u32 s0, s88, 0x1b98000
	s_addc_u32 s1, s89, 0
	v_writelane_b32 v253, s0, 16
	s_nop 1
	v_writelane_b32 v253, s1, 17
	s_add_u32 s0, s88, 0x1398000
	s_addc_u32 s1, s89, 0
	v_writelane_b32 v253, s0, 18
	s_nop 1
	v_writelane_b32 v253, s1, 19
	s_add_u32 s0, s88, 0x1318000
	s_addc_u32 s1, s89, 0
	v_writelane_b32 v253, s0, 20
	s_nop 1
	v_writelane_b32 v253, s1, 21
	s_add_u32 s0, s88, 0x1258000
	s_addc_u32 s1, s89, 0
	v_writelane_b32 v253, s0, 22
	s_nop 1
	v_writelane_b32 v253, s1, 23
	s_add_u32 s0, s88, 0x58000
	s_addc_u32 s1, s89, 0
	s_add_u32 s12, s88, 0x8198000
	v_writelane_b32 v253, s0, 24
	s_addc_u32 s13, s89, 0
	s_nop 0
	v_writelane_b32 v253, s1, 25
	s_add_u32 s0, s88, 0x12340000
	s_addc_u32 s1, s89, 0
	v_writelane_b32 v253, s0, 26
	s_cmpk_lt_i32 s90, 0x100
	s_nop 0
	v_writelane_b32 v253, s1, 27
	s_cselect_b64 s[0:1], -1, 0
	v_writelane_b32 v253, s0, 28
	s_nop 1
	v_writelane_b32 v253, s1, 29
	s_ashr_i32 s0, s90, 31
	v_writelane_b32 v253, s0, 30
	s_lshr_b32 s0, s0, 29
	s_add_i32 s0, s90, s0
	s_ashr_i32 s6, s0, 3
	s_and_b32 s0, s0, -8
	s_sub_i32 s2, s90, s0
	s_lshl_b32 s0, s2, 5
	s_add_u32 s4, s88, 0x14580000
	s_addc_u32 s5, s89, 0
	v_writelane_b32 v253, s4, 31
	s_cmpk_lt_i32 s90, 0x580
	s_mul_i32 s3, s2, 33
	v_writelane_b32 v253, s5, 32
	s_cselect_b64 s[4:5], -1, 0
	v_writelane_b32 v253, s4, 33
	s_cmp_lt_i32 s2, 0
	s_cselect_b32 s7, s3, s0
	v_writelane_b32 v253, s5, 34
	s_movk_i32 s4, 0xb1
	s_cselect_b32 s4, s4, 0xb0
	s_mul_i32 s4, s4, s2
	s_movk_i32 s5, 0x49
	s_cselect_b32 s5, s5, 0x48
	s_add_i32 s4, s4, s6
	s_mul_hi_i32 s0, s4, 0x2e8ba2e9
	s_lshr_b32 s3, s0, 31
	s_ashr_i32 s0, s0, 5
	s_add_i32 s0, s0, s3
	s_mul_i32 s3, s0, 0xb0
	s_sub_i32 s3, s4, s3
	s_lshl_b32 s8, s0, 3
	s_bfe_u32 s0, s3, 0x3001c
	s_add_i32 s4, s3, s0
	s_sext_i32_i16 s9, s4
	s_and_b32 s4, s4, 0xfff8
	s_sub_i32 s3, s3, s4
	s_sext_i32_i16 s3, s3
	s_lshr_b32 s0, s9, 3
	s_add_i32 s14, s8, s3
	s_ashr_i32 s3, s9, 3
	s_add_u32 s9, s88, 0x10340000
	s_addc_u32 s16, s89, 0
	s_add_u32 s18, s88, 0x14b00000
	v_writelane_b32 v253, s3, 35
	s_addc_u32 s19, s89, 0
	v_writelane_b32 v253, s18, 36
	s_mul_i32 s2, s5, s2
	s_mov_b32 s1, 0
	v_writelane_b32 v253, s19, 37
	s_add_u32 s18, s88, 0x15300000
	s_addc_u32 s19, s89, 0
	v_writelane_b32 v253, s18, 38
	s_nop 1
	v_writelane_b32 v253, s19, 39
	s_add_u32 s18, s88, 0xc998000
	s_addc_u32 s19, s89, 0
	v_writelane_b32 v253, s18, 40
	s_nop 1
	v_writelane_b32 v253, s19, 41
	s_add_u32 s18, s88, 0xe6c0000
	s_addc_u32 s19, s89, 0
	v_writelane_b32 v253, s18, 42
	s_nop 1
	v_writelane_b32 v253, s19, 43
	s_add_u32 s18, s88, 0xf2c0000
	s_addc_u32 s19, s89, 0
	v_writelane_b32 v253, s18, 44
	s_nop 1
	v_writelane_b32 v253, s19, 45
	s_add_u32 s18, s88, 0xfb00000
	s_addc_u32 s19, s89, 0
	v_writelane_b32 v253, s18, 46
	s_nop 1
	v_writelane_b32 v253, s19, 47
	s_add_u32 s18, s88, 0xe5b8000
	s_addc_u32 s19, s89, 0
	v_writelane_b32 v253, s18, 48
	s_add_u32 s3, s88, 0x5d98000
	s_nop 0
	v_writelane_b32 v253, s19, 49
	v_cmp_eq_u32_e64 s[18:19], 0, v0
	s_nop 1
	v_writelane_b32 v253, s18, 50
	s_nop 1
	v_writelane_b32 v253, s19, 51
	v_writelane_b32 v253, s3, 52
	s_addc_u32 s3, s89, 0
	v_writelane_b32 v253, s3, 53
	s_add_u32 s3, s88, 0x6098000
	v_writelane_b32 v253, s3, 54
	s_addc_u32 s3, s89, 0
	s_add_u32 s18, s88, 0xd998000
	v_writelane_b32 v253, s3, 55
	s_addc_u32 s19, s89, 0
	v_writelane_b32 v253, s18, 56
	s_nop 1
	v_writelane_b32 v253, s19, 57
	s_add_u32 s18, s88, 0xe198000
	s_addc_u32 s19, s89, 0
	v_writelane_b32 v253, s18, 58
	s_cmpk_lt_i32 s90, 0x200
	s_nop 0
	v_writelane_b32 v253, s19, 59
	s_cselect_b64 s[18:19], -1, 0
	v_writelane_b32 v253, s18, 60
	s_cmpk_lt_i32 s90, 0x240
	s_nop 0
	v_writelane_b32 v253, s19, 61
	s_cselect_b64 s[18:19], -1, 0
	s_add_i32 s2, s2, s6
	s_mul_hi_i32 s3, s2, 0x38e38e39
	s_lshr_b32 s4, s3, 31
	s_ashr_i32 s3, s3, 4
	s_add_i32 s3, s3, s4
	s_mul_i32 s4, s3, 0x48
	s_sub_i32 s4, s2, s4
	s_bfe_i32 s2, s4, 0x80000
	s_bfe_u32 s2, s2, 0x3000c
	s_add_i32 s5, s4, s2
	s_bfe_i32 s2, s5, 0x80000
	s_and_b32 s5, s5, 0xf8
	s_sub_i32 s4, s4, s5
	v_writelane_b32 v253, s18, 62
	s_lshl_b32 s3, s3, 3
	s_sext_i32_i16 s8, s2
	s_sext_i32_i8 s4, s4
	v_writelane_b32 v253, s19, 63
	s_add_i32 s18, s3, s4
	s_ashr_i32 s3, s8, 3
	s_lshr_b32 s2, s8, 3
	v_writelane_b32 v251, s3, 0
	s_mov_b32 s4, s18
	v_writelane_b32 v251, s4, 1
	s_bfe_i64 s[2:3], s[2:3], 0x100000
	s_ashr_i32 s19, s18, 31
	v_writelane_b32 v251, s5, 2
	s_lshl_b64 s[2:3], s[2:3], 19
	s_lshl_b64 s[4:5], s[18:19], 19
	v_writelane_b32 v251, s2, 3
	s_nop 1
	v_writelane_b32 v251, s3, 4
	s_add_u32 s2, s10, s4
	s_addc_u32 s3, s11, s5
	s_add_u32 s4, s2, 0x40000
	v_writelane_b32 v251, s2, 5
	s_addc_u32 s5, s3, 0
	s_cmpk_lt_i32 s90, 0x2ec
	v_writelane_b32 v251, s3, 6
	v_writelane_b32 v251, s4, 7
	s_cselect_b64 s[2:3], -1, 0
	s_nop 0
	v_writelane_b32 v251, s5, 8
	v_writelane_b32 v251, s2, 9
	s_nop 1
	v_writelane_b32 v251, s3, 10
	s_add_i32 s2, s7, s6
	s_ashr_i32 s3, s2, 31
	s_lshr_b32 s3, s3, 27
	s_add_i32 s3, s2, s3
	s_ashr_i32 s4, s3, 5
	s_and_b32 s3, s3, 0xffe0
	s_sub_i32 s3, s2, s3
	s_bfe_i32 s2, s3, 0x80000
	s_bfe_u32 s2, s2, 0x3000c
	s_add_i32 s5, s3, s2
	s_bfe_i32 s2, s5, 0x80000
	s_and_b32 s5, s5, 0xf8
	s_sub_i32 s3, s3, s5
	s_lshl_b32 s4, s4, 3
	s_sext_i32_i16 s6, s2
	s_sext_i32_i8 s3, s3
	s_lshr_b32 s2, s6, 3
	s_add_i32 s18, s4, s3
	s_ashr_i32 s3, s6, 3
	v_writelane_b32 v251, s3, 11
	s_ashr_i32 s19, s18, 31
	s_mul_i32 s5, s18, 0x160000
	s_bfe_i64 s[2:3], s[2:3], 0x100000
	s_mul_hi_i32 s4, s18, 0x160000
	s_add_u32 s6, s12, s5
	v_writelane_b32 v251, s12, 12
	s_addc_u32 s7, s13, s4
	s_add_u32 s4, s6, 0xb0000
	v_writelane_b32 v251, s13, 13
	v_writelane_b32 v251, s6, 14
	s_addc_u32 s5, s7, 0
	s_ashr_i32 s15, s14, 31
	v_writelane_b32 v251, s7, 15
	v_writelane_b32 v251, s4, 16
	s_bfe_i64 s[6:7], s[0:1], 0x100000
	s_lshl_b64 s[6:7], s[6:7], 19
	v_writelane_b32 v251, s5, 17
	s_mov_b32 s4, s14
	v_writelane_b32 v251, s4, 18
	s_mov_b32 s0, s18
	s_nop 0
	v_writelane_b32 v251, s5, 19
	v_writelane_b32 v251, s6, 20
	s_lshl_b64 s[4:5], s[14:15], 19
	s_add_u32 s4, s10, s4
	v_writelane_b32 v251, s7, 21
	v_writelane_b32 v251, s10, 22
	s_addc_u32 s5, s11, s5
	s_add_u32 s6, s4, 0x40000
	v_writelane_b32 v251, s11, 23
	v_writelane_b32 v251, s4, 24
	s_addc_u32 s7, s5, 0
	s_lshl_b64 s[2:3], s[2:3], 19
	v_writelane_b32 v251, s5, 25
	v_writelane_b32 v251, s6, 26
	s_lshl_b64 s[4:5], s[18:19], 19
	s_nop 0
	v_writelane_b32 v251, s7, 27
	v_writelane_b32 v251, s0, 28
	s_nop 1
	v_writelane_b32 v251, s1, 29
	v_writelane_b32 v251, s2, 30
	s_nop 1
	v_writelane_b32 v251, s3, 31
	v_writelane_b32 v251, s9, 32
	s_add_u32 s2, s9, s4
	v_writelane_b32 v251, s16, 33
	s_addc_u32 s3, s16, s5
	s_add_u32 s4, s2, 0x40000
	v_writelane_b32 v251, s2, 34
	s_addc_u32 s5, s3, 0
	s_lshl_b32 s0, s90, 11
	v_writelane_b32 v251, s3, 35
	v_writelane_b32 v251, s4, 36
	s_nop 1
	v_writelane_b32 v251, s5, 37
	v_writelane_b32 v251, s0, 38
	s_lshl_b32 s0, s90, 8
	v_writelane_b32 v251, s0, 39
	s_lshl_b32 s0, s90, 4
	v_writelane_b32 v251, s0, 40
	s_lshl_b32 s0, s90, 5
	v_writelane_b32 v251, s0, 41
	s_branch .LBB0_12
.LBB0_10:
	s_or_b64 exec, exec, s[36:37]
	s_waitcnt lgkmcnt(0)
	s_barrier

.LBB0_21:
	s_or_b64 exec, exec, s[14:15]
	s_waitcnt vmcnt(7)
	v_mul_f32_e32 v2, v35, v35
	v_fmac_f32_e32 v2, v34, v34
	v_fmac_f32_e32 v2, v36, v36
	v_fmac_f32_e32 v2, v37, v37
	s_waitcnt vmcnt(6)
	v_fmac_f32_e32 v2, v30, v30
	v_fmac_f32_e32 v2, v31, v31
	v_fmac_f32_e32 v2, v32, v32
	v_fmac_f32_e32 v2, v33, v33
	s_waitcnt vmcnt(5)
	v_fmac_f32_e32 v2, v10, v10
	v_fmac_f32_e32 v2, v11, v11
	v_fmac_f32_e32 v2, v12, v12
	v_fmac_f32_e32 v2, v13, v13
	s_waitcnt vmcnt(4)
	v_fmac_f32_e32 v2, v6, v6
	v_fmac_f32_e32 v2, v7, v7
	v_pk_mul_f32 v[4:5], v[8:9], v[8:9]
	global_store_dwordx4 v[94:95], v[34:37], off sc1
	global_store_dwordx4 v[94:95], v[30:33], off offset:1024 sc1
	global_store_dwordx4 v[94:95], v[10:13], off offset:2048 sc1
	global_store_dwordx4 v[94:95], v[6:9], off offset:3072 sc1
	v_add_f32_e32 v2, v4, v2
	v_add_f32_e32 v2, v5, v2
	v_add_u32_e32 v86, s6, v86
	s_movk_i32 s0, 0x3fff
	v_add_f32_dpp v2, v2, v2 row_ror:1 row_mask:0xf bank_mask:0xf bound_ctrl:1
	v_lshl_add_u64 v[92:93], v[92:93], 0, s[6:7]
	v_lshl_add_u64 v[94:95], v[94:95], 0, s[10:11]
	v_add_f32_dpp v2, v2, v2 row_ror:2 row_mask:0xf bank_mask:0xf bound_ctrl:1
	s_nop 1
	v_add_f32_dpp v2, v2, v2 row_ror:4 row_mask:0xf bank_mask:0xf bound_ctrl:1
	s_nop 1
	v_add_f32_dpp v2, v2, v2 row_ror:8 row_mask:0xf bank_mask:0xf bound_ctrl:1
	ds_bpermute_b32 v4, v96, v2
	s_waitcnt lgkmcnt(0)
	v_add_f32_e32 v2, v2, v4
	v_mov_b32_e32 v4, v2
	s_nop 1
	v_permlane32_swap_b32 v2, v4
	s_nop 1
	s_nop 0
	v_add_f32_e32 v2, v2, v4
	v_fmamk_f32 v2, v2, 0x3a800000, v1
	v_mul_f32_e32 v4, 0x4b800000, v2
	v_cmp_gt_f32_e32 vcc, s91, v2
	s_nop 1
	v_cndmask_b32_e32 v2, v2, v4, vcc
	v_rsq_f32_e32 v2, v2
	s_nop 0
	v_mul_f32_e32 v4, 0x45800000, v2
	v_cndmask_b32_e32 v2, v2, v4, vcc
	v_pk_mul_f32 v[4:5], v[34:35], v[2:3] op_sel_hi:[1,0]
	s_waitcnt vmcnt(7)
	v_pk_add_f32 v[34:35], v[54:55], 1.0 op_sel_hi:[1,0]
	s_waitcnt vmcnt(4)
	v_pk_mul_f32 v[4:5], v[26:27], v[4:5]
	v_cmp_lt_i32_e32 vcc, s0, v86
	v_pk_fma_f32 v[4:5], v[34:35], v[4:5], v[50:51]
	v_pk_mul_f32 v[34:35], v[36:37], v[2:3] op_sel_hi:[1,0]
	v_pk_add_f32 v[36:37], v[56:57], 1.0 op_sel_hi:[1,0]
	v_pk_mul_f32 v[34:35], v[28:29], v[34:35]
	v_cvt_pk_bf16_f32 v4, v4, v5
	v_pk_fma_f32 v[34:35], v[36:37], v[34:35], v[52:53]
	s_or_b64 s[12:13], vcc, s[12:13]
	v_cvt_pk_bf16_f32 v5, v34, v35
	global_store_dwordx2 v[90:91], v[4:5], off sc1
	v_pk_mul_f32 v[4:5], v[30:31], v[2:3] op_sel_hi:[1,0]
	v_pk_add_f32 v[30:31], v[42:43], 1.0 op_sel_hi:[1,0]
	v_pk_mul_f32 v[4:5], v[22:23], v[4:5]
	v_mov_b64_e32 v[34:35], v[62:63]
	v_pk_fma_f32 v[4:5], v[30:31], v[4:5], v[58:59]
	v_pk_mul_f32 v[30:31], v[32:33], v[2:3] op_sel_hi:[1,0]
	v_pk_add_f32 v[32:33], v[44:45], 1.0 op_sel_hi:[1,0]
	v_pk_mul_f32 v[30:31], v[24:25], v[30:31]
	v_cvt_pk_bf16_f32 v4, v4, v5
	v_pk_fma_f32 v[30:31], v[32:33], v[30:31], v[60:61]
	v_mov_b64_e32 v[36:37], v[64:65]
	v_cvt_pk_bf16_f32 v5, v30, v31
	global_store_dwordx2 v[90:91], v[4:5], off offset:512 sc1
	v_pk_mul_f32 v[4:5], v[10:11], v[2:3] op_sel_hi:[1,0]
	v_pk_add_f32 v[10:11], v[38:39], 1.0 op_sel_hi:[1,0]
	v_pk_mul_f32 v[4:5], v[18:19], v[4:5]
	v_mov_b64_e32 v[30:31], v[66:67]
	v_pk_fma_f32 v[4:5], v[10:11], v[4:5], v[74:75]
	v_pk_mul_f32 v[10:11], v[12:13], v[2:3] op_sel_hi:[1,0]
	v_pk_add_f32 v[12:13], v[40:41], 1.0 op_sel_hi:[1,0]
	v_pk_mul_f32 v[10:11], v[20:21], v[10:11]
	v_cvt_pk_bf16_f32 v4, v4, v5
	v_pk_fma_f32 v[10:11], v[12:13], v[10:11], v[76:77]
	v_mov_b64_e32 v[32:33], v[68:69]
	v_cvt_pk_bf16_f32 v5, v10, v11
	global_store_dwordx2 v[90:91], v[4:5], off offset:1024 sc1
	v_pk_mul_f32 v[4:5], v[6:7], v[2:3] op_sel_hi:[1,0]
	v_pk_add_f32 v[6:7], v[46:47], 1.0 op_sel_hi:[1,0]
	v_pk_mul_f32 v[4:5], v[14:15], v[4:5]
	v_mov_b64_e32 v[10:11], v[78:79]
	v_pk_fma_f32 v[4:5], v[6:7], v[4:5], v[70:71]
	v_pk_mul_f32 v[6:7], v[8:9], v[2:3] op_sel_hi:[1,0]
	v_pk_add_f32 v[8:9], v[48:49], 1.0 op_sel_hi:[1,0]
	v_pk_mul_f32 v[6:7], v[16:17], v[6:7]
	v_cvt_pk_bf16_f32 v4, v4, v5
	v_pk_fma_f32 v[6:7], v[8:9], v[6:7], v[72:73]
	v_mov_b64_e32 v[12:13], v[80:81]
	v_cvt_pk_bf16_f32 v5, v6, v7
	v_mov_b64_e32 v[6:7], v[82:83]
	global_store_dwordx2 v[90:91], v[4:5], off offset:1536 sc1
	v_lshl_add_u64 v[90:91], v[90:91], 0, s[8:9]
	v_mov_b64_e32 v[8:9], v[84:85]
	s_andn2_b64 exec, exec, s[12:13]
	s_cbranch_execz .LBB0_29

.LBB0_58:
	v_or_b32_e32 v142, 0x10000, v146
	v_add_u32_e32 v143, 0x10400, v146
	ds_read_b128 v[148:151], v142
	ds_read_b128 v[152:155], v143
	v_add_u32_e32 v142, 0x10800, v146
	v_add_u32_e32 v143, 0x10c00, v146
	ds_read_b128 v[156:159], v142
	ds_read_b128 v[160:163], v143
	s_add_u32 s10, s8, 0xfff50080
	s_addc_u32 s11, s9, -1
	s_cmp_eq_u32 s43, 40
	s_cselect_b32 s13, s5, s11
	s_cselect_b32 s12, s4, s10
	s_cselect_b32 s11, s7, s42
	s_cselect_b32 s10, s6, s41
	s_mov_b32 m0, s35
	v_lshl_add_u64 v[142:143], s[8:9], 0, v[138:139]
	ds_read_b128 v[164:167], v145
	ds_read_b128 v[168:171], v145 offset:1024
	ds_read_b128 v[172:175], v145 offset:2048
	ds_read_b128 v[176:179], v145 offset:3072
	ds_read_b128 v[194:197], v145 offset:4096
	ds_read_b128 v[198:201], v145 offset:5120
	ds_read_b128 v[202:205], v145 offset:6144
	ds_read_b128 v[206:209], v145 offset:7168
	global_load_lds_dwordx4 v[142:143], off
	v_lshl_add_u64 v[142:143], s[8:9], 0, v[140:141]
	s_mov_b32 m0, s36
	s_nop 0
	global_load_lds_dwordx4 v[142:143], off
	s_waitcnt lgkmcnt(8)
	s_barrier
	s_waitcnt lgkmcnt(0)
	s_setprio 1
	s_waitcnt lgkmcnt(0)
	v_mfma_f32_16x16x32_bf16 v[128:131], v[148:151], v[164:167], v[128:131]
	v_mfma_f32_16x16x32_bf16 v[124:127], v[156:159], v[164:167], v[124:127]
	v_mfma_f32_16x16x32_bf16 v[120:123], v[148:151], v[172:175], v[120:123]
	v_mfma_f32_16x16x32_bf16 v[112:115], v[156:159], v[172:175], v[112:115]
	v_mfma_f32_16x16x32_bf16 v[104:107], v[148:151], v[194:197], v[104:107]
	v_mfma_f32_16x16x32_bf16 v[96:99], v[156:159], v[194:197], v[96:99]
	v_mfma_f32_16x16x32_bf16 v[84:87], v[148:151], v[202:205], v[84:87]
	v_mfma_f32_16x16x32_bf16 v[76:79], v[156:159], v[202:205], v[76:79]
	v_mfma_f32_16x16x32_bf16 v[128:131], v[152:155], v[168:171], v[128:131]
	v_mfma_f32_16x16x32_bf16 v[124:127], v[160:163], v[168:171], v[124:127]
	v_mfma_f32_16x16x32_bf16 v[120:123], v[152:155], v[176:179], v[120:123]
	v_mfma_f32_16x16x32_bf16 v[112:115], v[160:163], v[176:179], v[112:115]
	v_mfma_f32_16x16x32_bf16 v[104:107], v[152:155], v[198:201], v[104:107]
	v_mfma_f32_16x16x32_bf16 v[96:99], v[160:163], v[198:201], v[96:99]
	v_mfma_f32_16x16x32_bf16 v[84:87], v[152:155], v[206:209], v[84:87]
	v_mfma_f32_16x16x32_bf16 v[76:79], v[160:163], v[206:209], v[76:79]
	s_setprio 0
	s_barrier
	v_or_b32_e32 v142, 0x14000, v146
	v_add_u32_e32 v143, 0x14400, v146
	ds_read_b128 v[210:213], v142
	ds_read_b128 v[214:217], v143
	v_add_u32_e32 v142, 0x14800, v146
	v_add_u32_e32 v143, 0x14c00, v146
	s_mov_b32 m0, s17
	ds_read_b128 v[218:221], v142
	ds_read_b128 v[222:225], v143
	v_lshl_add_u64 v[142:143], s[10:11], 0, v[2:3]
	global_load_lds_dwordx4 v[142:143], off
	v_lshl_add_u64 v[240:241], s[10:11], 0, v[132:133]
	s_mov_b32 m0, s18
	s_nop 0
	global_load_lds_dwordx4 v[240:241], off
	s_barrier
	s_waitcnt lgkmcnt(0)
	s_setprio 1
	s_waitcnt lgkmcnt(0)
	v_mfma_f32_16x16x32_bf16 v[116:119], v[210:213], v[164:167], v[116:119]
	v_mfma_f32_16x16x32_bf16 v[108:111], v[218:221], v[164:167], v[108:111]
	v_mfma_f32_16x16x32_bf16 v[100:103], v[210:213], v[172:175], v[100:103]
	v_mfma_f32_16x16x32_bf16 v[92:95], v[218:221], v[172:175], v[92:95]
	v_mfma_f32_16x16x32_bf16 v[88:91], v[210:213], v[194:197], v[88:91]
	v_mfma_f32_16x16x32_bf16 v[80:83], v[218:221], v[194:197], v[80:83]
	v_mfma_f32_16x16x32_bf16 v[72:75], v[210:213], v[202:205], v[72:75]
	v_mfma_f32_16x16x32_bf16 v[68:71], v[218:221], v[202:205], v[68:71]
	v_mfma_f32_16x16x32_bf16 v[116:119], v[214:217], v[168:171], v[116:119]
	v_mfma_f32_16x16x32_bf16 v[108:111], v[222:225], v[168:171], v[108:111]
	v_mfma_f32_16x16x32_bf16 v[100:103], v[214:217], v[176:179], v[100:103]
	v_mfma_f32_16x16x32_bf16 v[92:95], v[222:225], v[176:179], v[92:95]
	v_mfma_f32_16x16x32_bf16 v[88:91], v[214:217], v[198:201], v[88:91]
	v_mfma_f32_16x16x32_bf16 v[80:83], v[222:225], v[198:201], v[80:83]
	v_mfma_f32_16x16x32_bf16 v[72:75], v[214:217], v[206:209], v[72:75]
	v_mfma_f32_16x16x32_bf16 v[68:71], v[222:225], v[206:209], v[68:71]
	s_setprio 0
	s_mov_b32 m0, s16
	v_lshl_add_u64 v[242:243], s[12:13], 0, v[136:137]
	s_barrier
	ds_read_b128 v[164:167], v145 offset:16384
	ds_read_b128 v[168:171], v145 offset:17408
	ds_read_b128 v[172:175], v145 offset:18432
	ds_read_b128 v[176:179], v145 offset:19456
	ds_read_b128 v[194:197], v145 offset:20480
	ds_read_b128 v[198:201], v145 offset:21504
	ds_read_b128 v[202:205], v145 offset:22528
	ds_read_b128 v[206:209], v145 offset:23552
	global_load_lds_dwordx4 v[242:243], off
	v_lshl_add_u64 v[244:245], s[12:13], 0, v[134:135]
	s_mov_b32 m0, s19
	s_nop 0
	global_load_lds_dwordx4 v[244:245], off
	s_barrier
	s_waitcnt lgkmcnt(0)
	s_setprio 1
	s_waitcnt lgkmcnt(0)
	v_mfma_f32_16x16x32_bf16 v[64:67], v[148:151], v[164:167], v[64:67]
	v_mfma_f32_16x16x32_bf16 v[60:63], v[156:159], v[164:167], v[60:63]
	v_mfma_f32_16x16x32_bf16 v[56:59], v[148:151], v[172:175], v[56:59]
	v_mfma_f32_16x16x32_bf16 v[48:51], v[156:159], v[172:175], v[48:51]
	v_mfma_f32_16x16x32_bf16 v[40:43], v[148:151], v[194:197], v[40:43]
	v_mfma_f32_16x16x32_bf16 v[32:35], v[156:159], v[194:197], v[32:35]
	v_mfma_f32_16x16x32_bf16 v[24:27], v[148:151], v[202:205], v[24:27]
	v_mfma_f32_16x16x32_bf16 v[16:19], v[156:159], v[202:205], v[16:19]
	v_mfma_f32_16x16x32_bf16 v[64:67], v[152:155], v[168:171], v[64:67]
	v_mfma_f32_16x16x32_bf16 v[60:63], v[160:163], v[168:171], v[60:63]
	v_mfma_f32_16x16x32_bf16 v[56:59], v[152:155], v[176:179], v[56:59]
	v_mfma_f32_16x16x32_bf16 v[48:51], v[160:163], v[176:179], v[48:51]
	v_mfma_f32_16x16x32_bf16 v[40:43], v[152:155], v[198:201], v[40:43]
	v_mfma_f32_16x16x32_bf16 v[32:35], v[160:163], v[198:201], v[32:35]
	v_mfma_f32_16x16x32_bf16 v[24:27], v[152:155], v[206:209], v[24:27]
	v_mfma_f32_16x16x32_bf16 v[16:19], v[160:163], v[206:209], v[16:19]
	s_setprio 0
	s_barrier
	s_add_u32 s44, s10, 0xb0000
	s_addc_u32 s45, s11, 0
	s_mov_b32 m0, s20
	v_lshl_add_u64 v[148:149], s[44:45], 0, v[2:3]
	global_load_lds_dwordx4 v[148:149], off
	v_lshl_add_u64 v[148:149], s[44:45], 0, v[132:133]
	s_mov_b32 m0, s21
	s_nop 0
	global_load_lds_dwordx4 v[148:149], off
	s_waitcnt vmcnt(6)
	s_barrier
	s_setprio 1
	v_mfma_f32_16x16x32_bf16 v[52:55], v[210:213], v[164:167], v[52:55]
	v_mfma_f32_16x16x32_bf16 v[44:47], v[218:221], v[164:167], v[44:47]
	v_mfma_f32_16x16x32_bf16 v[36:39], v[210:213], v[172:175], v[36:39]
	v_mfma_f32_16x16x32_bf16 v[28:31], v[218:221], v[172:175], v[28:31]
	v_mfma_f32_16x16x32_bf16 v[20:23], v[210:213], v[194:197], v[20:23]
	v_mfma_f32_16x16x32_bf16 v[12:15], v[218:221], v[194:197], v[12:15]
	v_mfma_f32_16x16x32_bf16 v[8:11], v[210:213], v[202:205], v[8:11]
	v_mfma_f32_16x16x32_bf16 v[4:7], v[218:221], v[202:205], v[4:7]
	v_mfma_f32_16x16x32_bf16 v[52:55], v[214:217], v[168:171], v[52:55]
	v_mfma_f32_16x16x32_bf16 v[44:47], v[222:225], v[168:171], v[44:47]
	v_mfma_f32_16x16x32_bf16 v[36:39], v[214:217], v[176:179], v[36:39]
	v_mfma_f32_16x16x32_bf16 v[28:31], v[222:225], v[176:179], v[28:31]
	v_mfma_f32_16x16x32_bf16 v[20:23], v[214:217], v[198:201], v[20:23]
	v_mfma_f32_16x16x32_bf16 v[12:15], v[222:225], v[198:201], v[12:15]
	v_mfma_f32_16x16x32_bf16 v[8:11], v[214:217], v[206:209], v[8:11]
	v_mfma_f32_16x16x32_bf16 v[4:7], v[222:225], v[206:209], v[4:7]
	s_setprio 0
	v_or_b32_e32 v148, 0x18000, v146
	v_add_u32_e32 v152, 0x18400, v146
	v_add_u32_e32 v156, 0x18800, v146
	v_add_u32_e32 v160, 0x18c00, v146
	s_barrier
	ds_read_b128 v[148:151], v148
	ds_read_b128 v[152:155], v152
	ds_read_b128 v[156:159], v156
	ds_read_b128 v[160:163], v160
	s_add_u32 s12, s12, 0xb0000
	s_addc_u32 s13, s13, 0
	s_mov_b32 m0, s22
	v_lshl_add_u64 v[210:211], s[12:13], 0, v[136:137]
	ds_read_b128 v[164:167], v145 offset:32768
	ds_read_b128 v[168:171], v145 offset:33792
	ds_read_b128 v[172:175], v145 offset:34816
	ds_read_b128 v[176:179], v145 offset:35840
	ds_read_b128 v[194:197], v145 offset:36864
	ds_read_b128 v[198:201], v145 offset:37888
	ds_read_b128 v[202:205], v145 offset:38912
	ds_read_b128 v[206:209], v145 offset:39936
	global_load_lds_dwordx4 v[210:211], off
	v_lshl_add_u64 v[210:211], s[12:13], 0, v[134:135]
	s_mov_b32 m0, s23
	s_nop 0
	global_load_lds_dwordx4 v[210:211], off
	s_waitcnt lgkmcnt(8)
	s_barrier
	s_waitcnt lgkmcnt(0)
	s_setprio 1
	s_waitcnt lgkmcnt(0)
	v_mfma_f32_16x16x32_bf16 v[128:131], v[148:151], v[164:167], v[128:131]
	v_mfma_f32_16x16x32_bf16 v[124:127], v[156:159], v[164:167], v[124:127]
	v_mfma_f32_16x16x32_bf16 v[120:123], v[148:151], v[172:175], v[120:123]
	v_mfma_f32_16x16x32_bf16 v[112:115], v[156:159], v[172:175], v[112:115]
	v_mfma_f32_16x16x32_bf16 v[104:107], v[148:151], v[194:197], v[104:107]
	v_mfma_f32_16x16x32_bf16 v[96:99], v[156:159], v[194:197], v[96:99]
	v_mfma_f32_16x16x32_bf16 v[84:87], v[148:151], v[202:205], v[84:87]
	v_mfma_f32_16x16x32_bf16 v[76:79], v[156:159], v[202:205], v[76:79]
	v_mfma_f32_16x16x32_bf16 v[128:131], v[152:155], v[168:171], v[128:131]
	v_mfma_f32_16x16x32_bf16 v[124:127], v[160:163], v[168:171], v[124:127]
	v_mfma_f32_16x16x32_bf16 v[120:123], v[152:155], v[176:179], v[120:123]
	v_mfma_f32_16x16x32_bf16 v[112:115], v[160:163], v[176:179], v[112:115]
	v_mfma_f32_16x16x32_bf16 v[104:107], v[152:155], v[198:201], v[104:107]
	v_mfma_f32_16x16x32_bf16 v[96:99], v[160:163], v[198:201], v[96:99]
	v_mfma_f32_16x16x32_bf16 v[84:87], v[152:155], v[206:209], v[84:87]
	v_mfma_f32_16x16x32_bf16 v[76:79], v[160:163], v[206:209], v[76:79]
	s_setprio 0
	s_barrier
	v_or_b32_e32 v189, 0x1c000, v146
	v_add_u32_e32 v214, 0x1c400, v146
	s_mov_b32 m0, s25
	ds_read_b128 v[210:213], v189
	ds_read_b128 v[214:217], v214
	v_add_u32_e32 v189, 0x1c800, v146
	v_add_u32_e32 v222, 0x1cc00, v146
	v_lshl_add_u64 v[142:143], v[142:143], 0, s[82:83]
	ds_read_b128 v[218:221], v189
	ds_read_b128 v[222:225], v222
	global_load_lds_dwordx4 v[142:143], off
	v_lshl_add_u64 v[142:143], v[240:241], 0, s[82:83]
	s_mov_b32 m0, s26
	s_nop 0
	global_load_lds_dwordx4 v[142:143], off
	s_barrier
	s_waitcnt lgkmcnt(0)
	s_setprio 1
	s_waitcnt lgkmcnt(0)
	v_mfma_f32_16x16x32_bf16 v[116:119], v[210:213], v[164:167], v[116:119]
	v_mfma_f32_16x16x32_bf16 v[108:111], v[218:221], v[164:167], v[108:111]
	v_mfma_f32_16x16x32_bf16 v[100:103], v[210:213], v[172:175], v[100:103]
	v_mfma_f32_16x16x32_bf16 v[92:95], v[218:221], v[172:175], v[92:95]
	v_mfma_f32_16x16x32_bf16 v[88:91], v[210:213], v[194:197], v[88:91]
	v_mfma_f32_16x16x32_bf16 v[80:83], v[218:221], v[194:197], v[80:83]
	v_mfma_f32_16x16x32_bf16 v[72:75], v[210:213], v[202:205], v[72:75]
	v_mfma_f32_16x16x32_bf16 v[68:71], v[218:221], v[202:205], v[68:71]
	v_mfma_f32_16x16x32_bf16 v[116:119], v[214:217], v[168:171], v[116:119]
	v_mfma_f32_16x16x32_bf16 v[108:111], v[222:225], v[168:171], v[108:111]
	v_mfma_f32_16x16x32_bf16 v[100:103], v[214:217], v[176:179], v[100:103]
	v_mfma_f32_16x16x32_bf16 v[92:95], v[222:225], v[176:179], v[92:95]
	v_mfma_f32_16x16x32_bf16 v[88:91], v[214:217], v[198:201], v[88:91]
	v_mfma_f32_16x16x32_bf16 v[80:83], v[222:225], v[198:201], v[80:83]
	v_mfma_f32_16x16x32_bf16 v[72:75], v[214:217], v[206:209], v[72:75]
	v_mfma_f32_16x16x32_bf16 v[68:71], v[222:225], v[206:209], v[68:71]
	s_setprio 0
	s_mov_b32 m0, s27
	v_lshl_add_u64 v[142:143], v[242:243], 0, s[82:83]
	s_barrier
	ds_read_b128 v[164:167], v145 offset:49152
	ds_read_b128 v[168:171], v145 offset:50176
	ds_read_b128 v[172:175], v145 offset:51200
	ds_read_b128 v[176:179], v145 offset:52224
	ds_read_b128 v[194:197], v145 offset:53248
	ds_read_b128 v[198:201], v145 offset:54272
	ds_read_b128 v[202:205], v145 offset:55296
	ds_read_b128 v[206:209], v145 offset:56320
	global_load_lds_dwordx4 v[142:143], off
	v_lshl_add_u64 v[142:143], v[244:245], 0, s[82:83]
	s_mov_b32 m0, s28
	s_nop 0
	global_load_lds_dwordx4 v[142:143], off
	s_barrier
	s_waitcnt lgkmcnt(0)
	s_setprio 1
	s_waitcnt lgkmcnt(0)
	v_mfma_f32_16x16x32_bf16 v[64:67], v[148:151], v[164:167], v[64:67]
	v_mfma_f32_16x16x32_bf16 v[60:63], v[156:159], v[164:167], v[60:63]
	v_mfma_f32_16x16x32_bf16 v[56:59], v[148:151], v[172:175], v[56:59]
	v_mfma_f32_16x16x32_bf16 v[48:51], v[156:159], v[172:175], v[48:51]
	v_mfma_f32_16x16x32_bf16 v[40:43], v[148:151], v[194:197], v[40:43]
	v_mfma_f32_16x16x32_bf16 v[32:35], v[156:159], v[194:197], v[32:35]
	v_mfma_f32_16x16x32_bf16 v[24:27], v[148:151], v[202:205], v[24:27]
	v_mfma_f32_16x16x32_bf16 v[16:19], v[156:159], v[202:205], v[16:19]
	v_mfma_f32_16x16x32_bf16 v[64:67], v[152:155], v[168:171], v[64:67]
	v_mfma_f32_16x16x32_bf16 v[60:63], v[160:163], v[168:171], v[60:63]
	v_mfma_f32_16x16x32_bf16 v[56:59], v[152:155], v[176:179], v[56:59]
	v_mfma_f32_16x16x32_bf16 v[48:51], v[160:163], v[176:179], v[48:51]
	v_mfma_f32_16x16x32_bf16 v[40:43], v[152:155], v[198:201], v[40:43]
	v_mfma_f32_16x16x32_bf16 v[32:35], v[160:163], v[198:201], v[32:35]
	v_mfma_f32_16x16x32_bf16 v[24:27], v[152:155], v[206:209], v[24:27]
	v_mfma_f32_16x16x32_bf16 v[16:19], v[160:163], v[206:209], v[16:19]
	s_setprio 0
	s_barrier
	s_add_u32 s10, s10, 0xb0080
	s_addc_u32 s11, s11, 0
	s_mov_b32 m0, s29
	v_lshl_add_u64 v[142:143], s[10:11], 0, v[2:3]
	global_load_lds_dwordx4 v[142:143], off
	v_lshl_add_u64 v[142:143], s[10:11], 0, v[132:133]
	s_mov_b32 m0, s30
	s_nop 0
	global_load_lds_dwordx4 v[142:143], off
	s_waitcnt vmcnt(6)
	s_barrier
	s_setprio 1
	v_mfma_f32_16x16x32_bf16 v[52:55], v[210:213], v[164:167], v[52:55]
	v_mfma_f32_16x16x32_bf16 v[44:47], v[218:221], v[164:167], v[44:47]
	v_mfma_f32_16x16x32_bf16 v[36:39], v[210:213], v[172:175], v[36:39]
	v_mfma_f32_16x16x32_bf16 v[28:31], v[218:221], v[172:175], v[28:31]
	v_mfma_f32_16x16x32_bf16 v[20:23], v[210:213], v[194:197], v[20:23]
	v_mfma_f32_16x16x32_bf16 v[12:15], v[218:221], v[194:197], v[12:15]
	v_mfma_f32_16x16x32_bf16 v[8:11], v[210:213], v[202:205], v[8:11]
	v_mfma_f32_16x16x32_bf16 v[4:7], v[218:221], v[202:205], v[4:7]
	v_mfma_f32_16x16x32_bf16 v[52:55], v[214:217], v[168:171], v[52:55]
	v_mfma_f32_16x16x32_bf16 v[44:47], v[222:225], v[168:171], v[44:47]
	v_mfma_f32_16x16x32_bf16 v[36:39], v[214:217], v[176:179], v[36:39]
	v_mfma_f32_16x16x32_bf16 v[28:31], v[222:225], v[176:179], v[28:31]
	v_mfma_f32_16x16x32_bf16 v[20:23], v[214:217], v[198:201], v[20:23]
	v_mfma_f32_16x16x32_bf16 v[12:15], v[222:225], v[198:201], v[12:15]
	v_mfma_f32_16x16x32_bf16 v[8:11], v[214:217], v[206:209], v[8:11]
	v_mfma_f32_16x16x32_bf16 v[4:7], v[222:225], v[206:209], v[4:7]
	s_setprio 0
	s_add_i32 s43, s43, 2
	s_add_u32 s8, s8, 0x100
	s_addc_u32 s9, s9, 0
	s_add_u32 s41, s41, 0x100
	s_addc_u32 s42, s42, 0
	s_cmp_gt_u32 s43, 41
	s_barrier
	s_cbranch_scc0 .LBB0_58
	v_lshl_add_u32 v148, s40, 8, v144
	v_lshl_or_b32 v142, s39, 8, v147
	v_ashrrev_i32_e32 v149, 31, v148
	v_readlane_b32 s8, v253, 26
	v_ashrrev_i32_e32 v143, 31, v142
	v_lshlrev_b64 v[150:151], 11, v[148:149]
	v_readlane_b32 s9, v253, 27
	v_lshlrev_b64 v[152:153], 1, v[142:143]
	v_cvt_pk_bf16_f32 v128, v128, v129
	v_cvt_pk_bf16_f32 v129, v130, v131
	v_cvt_pk_bf16_f32 v130, v124, v125
	v_cvt_pk_bf16_f32 v131, v126, v127
	s_nop 0
	v_lshl_add_u64 v[150:151], s[8:9], 0, v[150:151]
	v_lshl_add_u64 v[142:143], v[150:151], 0, v[152:153]
	global_store_dwordx4 v[142:143], v[128:131], off sc1
	v_cvt_pk_bf16_f32 v116, v116, v117
	v_cvt_pk_bf16_f32 v117, v118, v119
	v_cvt_pk_bf16_f32 v118, v108, v109
	v_or_b32_e32 v108, 16, v148
	v_ashrrev_i32_e32 v109, 31, v108
	v_lshlrev_b64 v[108:109], 11, v[108:109]
	v_lshl_add_u64 v[108:109], s[8:9], 0, v[108:109]
	v_cvt_pk_bf16_f32 v119, v110, v111
	global_store_dwordx4 v[142:143], v[116:119], off offset:256 sc1
	s_mov_b32 s39, s37
	s_mov_b32 s40, s38
	v_lshl_add_u64 v[116:117], v[108:109], 0, v[152:153]
	v_cvt_pk_bf16_f32 v108, v120, v121
	v_cvt_pk_bf16_f32 v109, v122, v123
	v_cvt_pk_bf16_f32 v110, v112, v113
	v_cvt_pk_bf16_f32 v111, v114, v115
	global_store_dwordx4 v[116:117], v[108:111], off sc1
	v_cvt_pk_bf16_f32 v100, v100, v101
	v_cvt_pk_bf16_f32 v101, v102, v103
	v_cvt_pk_bf16_f32 v102, v92, v93
	v_or_b32_e32 v92, 32, v148
	v_ashrrev_i32_e32 v93, 31, v92
	v_lshlrev_b64 v[92:93], 11, v[92:93]
	v_lshl_add_u64 v[92:93], s[8:9], 0, v[92:93]
	v_cvt_pk_bf16_f32 v103, v94, v95
	global_store_dwordx4 v[116:117], v[100:103], off offset:256 sc1
	s_mov_b64 s[10:11], s[6:7]
	s_nop 0
	v_lshl_add_u64 v[100:101], v[92:93], 0, v[152:153]
	v_cvt_pk_bf16_f32 v92, v104, v105
	v_cvt_pk_bf16_f32 v93, v106, v107
	v_cvt_pk_bf16_f32 v94, v96, v97
	v_cvt_pk_bf16_f32 v95, v98, v99
	global_store_dwordx4 v[100:101], v[92:95], off sc1
	v_cvt_pk_bf16_f32 v88, v88, v89
	v_cvt_pk_bf16_f32 v89, v90, v91
	v_cvt_pk_bf16_f32 v90, v80, v81
	v_or_b32_e32 v80, 48, v148
	v_ashrrev_i32_e32 v81, 31, v80
	v_lshlrev_b64 v[80:81], 11, v[80:81]
	v_lshl_add_u64 v[80:81], s[8:9], 0, v[80:81]
	v_cvt_pk_bf16_f32 v91, v82, v83
	global_store_dwordx4 v[100:101], v[88:91], off offset:256 sc1
	s_mov_b64 s[8:9], 0x40000
	s_nop 0
	v_lshl_add_u64 v[88:89], v[80:81], 0, v[152:153]
	v_cvt_pk_bf16_f32 v80, v84, v85
	v_cvt_pk_bf16_f32 v81, v86, v87
	v_cvt_pk_bf16_f32 v82, v76, v77
	v_cvt_pk_bf16_f32 v83, v78, v79
	global_store_dwordx4 v[88:89], v[80:83], off sc1
	v_cvt_pk_bf16_f32 v72, v72, v73
	v_cvt_pk_bf16_f32 v73, v74, v75
	v_cvt_pk_bf16_f32 v74, v68, v69
	v_lshl_add_u64 v[68:69], v[142:143], 0, s[8:9]
	s_mov_b32 s8, 0x40000
	v_cvt_pk_bf16_f32 v75, v70, v71
	global_store_dwordx4 v[88:89], v[72:75], off offset:256 sc1
	v_cvt_pk_bf16_f32 v64, v64, v65
	v_cvt_pk_bf16_f32 v65, v66, v67
	v_cvt_pk_bf16_f32 v66, v60, v61
	v_add_co_u32_e32 v60, vcc, s8, v142
	v_cvt_pk_bf16_f32 v67, v62, v63
	s_mov_b64 s[8:9], 0x48000
	s_nop 0
	v_addc_co_u32_e32 v61, vcc, 0, v143, vcc
	global_store_dwordx4 v[60:61], v[64:67], off sc1
	v_cvt_pk_bf16_f32 v52, v52, v53
	v_cvt_pk_bf16_f32 v53, v54, v55
	v_cvt_pk_bf16_f32 v54, v44, v45
	v_cvt_pk_bf16_f32 v55, v46, v47
	global_store_dwordx4 v[68:69], v[52:55], off offset:256 sc1
	v_cvt_pk_bf16_f32 v44, v56, v57
	v_cvt_pk_bf16_f32 v45, v58, v59
	v_cvt_pk_bf16_f32 v46, v48, v49
	v_cvt_pk_bf16_f32 v47, v50, v51
	s_nop 1
	v_lshl_add_u64 v[52:53], v[142:143], 0, s[8:9]
	s_mov_b32 s8, 0x48000
	v_add_co_u32_e32 v48, vcc, s8, v142
	s_mov_b64 s[8:9], 0x50000
	s_nop 0
	v_addc_co_u32_e32 v49, vcc, 0, v143, vcc
	global_store_dwordx4 v[48:49], v[44:47], off sc1
	v_cvt_pk_bf16_f32 v36, v36, v37
	v_cvt_pk_bf16_f32 v37, v38, v39
	v_cvt_pk_bf16_f32 v38, v28, v29
	v_cvt_pk_bf16_f32 v39, v30, v31
	global_store_dwordx4 v[52:53], v[36:39], off offset:256 sc1
	v_cvt_pk_bf16_f32 v28, v40, v41
	v_cvt_pk_bf16_f32 v29, v42, v43
	v_cvt_pk_bf16_f32 v30, v32, v33
	v_cvt_pk_bf16_f32 v31, v34, v35
	s_nop 1
	v_lshl_add_u64 v[36:37], v[142:143], 0, s[8:9]
	s_mov_b32 s8, 0x50000
	v_add_co_u32_e32 v32, vcc, s8, v142
	s_mov_b64 s[8:9], 0x58000
	s_nop 0
	v_addc_co_u32_e32 v33, vcc, 0, v143, vcc
	global_store_dwordx4 v[32:33], v[28:31], off sc1
	v_cvt_pk_bf16_f32 v20, v20, v21
	v_cvt_pk_bf16_f32 v21, v22, v23
	v_cvt_pk_bf16_f32 v22, v12, v13
	v_cvt_pk_bf16_f32 v23, v14, v15
	global_store_dwordx4 v[36:37], v[20:23], off offset:256 sc1
	v_cvt_pk_bf16_f32 v12, v24, v25
	v_cvt_pk_bf16_f32 v13, v26, v27
	v_cvt_pk_bf16_f32 v14, v16, v17
	v_cvt_pk_bf16_f32 v15, v18, v19
	s_nop 1
	v_lshl_add_u64 v[20:21], v[142:143], 0, s[8:9]
	s_mov_b32 s8, 0x58000
	v_add_co_u32_e32 v16, vcc, s8, v142
	s_mov_b64 s[8:9], s[4:5]
	s_nop 0
	v_addc_co_u32_e32 v17, vcc, 0, v143, vcc
	s_and_b64 vcc, exec, s[2:3]
	global_store_dwordx4 v[16:17], v[12:15], off sc1
	v_cvt_pk_bf16_f32 v8, v8, v9
	v_cvt_pk_bf16_f32 v9, v10, v11
	v_cvt_pk_bf16_f32 v10, v4, v5
	v_cvt_pk_bf16_f32 v11, v6, v7
	global_store_dwordx4 v[20:21], v[8:11], off offset:256 sc1
	s_cbranch_vccz .LBB0_47
	s_waitcnt vmcnt(0)
	s_cmpk_gt_u32 s0, 0xff
	v_readlane_b32 s34, v251, 48
	s_cbranch_scc1 .LBB0_62
	s_barrier

.LBB0_274:
	s_or_b64 exec, exec, s[14:15]
	v_lshlrev_b32_e32 v150, 16, v142
	v_and_b32_e32 v151, 0xffff0000, v142
	v_lshlrev_b32_e32 v158, 16, v140
	v_and_b32_e32 v159, 0xffff0000, v140
	v_and_b32_e32 v165, 0xffff0000, v136
	v_and_b32_e32 v167, 0xffff0000, v134
	v_pk_mul_f32 v[154:155], v[150:151], v[150:151]
	v_lshlrev_b32_e32 v142, 16, v143
	v_and_b32_e32 v143, 0xffff0000, v143
	v_pk_mul_f32 v[160:161], v[158:159], v[158:159]
	v_lshlrev_b32_e32 v140, 16, v141
	v_and_b32_e32 v141, 0xffff0000, v141
	v_lshlrev_b32_e32 v164, 16, v136
	v_lshlrev_b32_e32 v166, 16, v134
	v_mov_b32_e32 v170, v167
	v_mov_b32_e32 v171, v165
	v_pk_mul_f32 v[156:157], v[142:143], v[142:143]
	v_pk_mul_f32 v[162:163], v[140:141], v[140:141]
	v_lshlrev_b32_e32 v136, 16, v137
	v_lshlrev_b32_e32 v134, 16, v135
	v_mov_b32_e32 v168, v166
	v_mov_b32_e32 v169, v164
	v_pk_mul_f32 v[170:171], v[170:171], v[170:171]
	v_add_f32_e32 v154, v154, v155
	v_add_f32_e32 v155, v160, v161
	v_and_b32_e32 v137, 0xffff0000, v137
	v_and_b32_e32 v135, 0xffff0000, v135
	v_pk_fma_f32 v[168:169], v[168:169], v[168:169], v[170:171]
	v_mov_b32_e32 v170, v134
	v_mov_b32_e32 v171, v136
	v_add_f32_e32 v154, v156, v154
	v_add_f32_e32 v155, v162, v155
	v_mov_b32_e32 v172, v135
	v_mov_b32_e32 v173, v137
	v_pk_fma_f32 v[168:169], v[170:171], v[170:171], v[168:169]
	v_add_f32_e32 v154, v157, v154
	v_add_f32_e32 v155, v163, v155
	v_pk_fma_f32 v[168:169], v[172:173], v[172:173], v[168:169]
	v_add_f32_e32 v154, v155, v154
	v_add_f32_e32 v154, v169, v154
	v_add_f32_e32 v154, v168, v154
	v_lshl_add_u64 v[4:5], v[130:131], 0, v[120:121]
	s_mov_b32 s0, 0x6198000
	v_add_f32_dpp v154, v154, v154 row_ror:1 row_mask:0xf bank_mask:0xf bound_ctrl:1
	s_and_b64 s[2:3], exec, s[2:3]
	s_or_b64 s[12:13], s[2:3], s[12:13]
	v_add_f32_dpp v154, v154, v154 row_ror:2 row_mask:0xf bank_mask:0xf bound_ctrl:1
	v_lshl_add_u64 v[128:129], v[128:129], 0, s[10:11]
	v_lshl_add_u64 v[130:131], v[130:131], 0, s[10:11]
	v_add_f32_dpp v154, v154, v154 row_ror:4 row_mask:0xf bank_mask:0xf bound_ctrl:1
	v_lshl_add_u64 v[132:133], v[132:133], 0, s[8:9]
	s_nop 0
	v_add_f32_dpp v154, v154, v154 row_ror:8 row_mask:0xf bank_mask:0xf bound_ctrl:1
	ds_bpermute_b32 v155, v152, v154
	s_waitcnt lgkmcnt(0)
	v_add_f32_e32 v154, v154, v155
	v_mov_b32_e32 v155, v154
	s_nop 1
	v_permlane32_swap_b32 v155, v154
	s_nop 1
	s_nop 0
	v_add_f32_e32 v154, v155, v154
	v_fmamk_f32 v154, v154, 0x3a800000, v1
	v_cmp_gt_f32_e32 vcc, s91, v154
	v_mul_f32_e32 v155, 0x4b800000, v154
	s_nop 0
	v_cndmask_b32_e32 v154, v154, v155, vcc
	v_rsq_f32_e32 v154, v154
	s_nop 0
	v_mul_f32_e32 v155, 0x45800000, v154
	v_cndmask_b32_e32 v154, v154, v155, vcc
	v_pk_mul_f32 v[142:143], v[154:155], v[142:143] op_sel_hi:[0,1]
	v_pk_mul_f32 v[140:141], v[154:155], v[140:141] op_sel_hi:[0,1]
	v_pk_mul_f32 v[136:137], v[154:155], v[136:137] op_sel_hi:[0,1]
	v_pk_mul_f32 v[150:151], v[154:155], v[150:151] op_sel_hi:[0,1]
	v_pk_mul_f32 v[142:143], v[36:37], v[142:143]
	v_pk_mul_f32 v[140:141], v[28:29], v[140:141]
	v_pk_mul_f32 v[136:137], v[20:21], v[136:137]
	v_pk_mul_f32 v[150:151], v[34:35], v[150:151]
	s_waitcnt vmcnt(9)
	v_pk_fma_f32 v[44:45], v[76:77], v[142:143], v[44:45]
	v_pk_mul_f32 v[142:143], v[154:155], v[158:159] op_sel_hi:[0,1]
	s_waitcnt vmcnt(8)
	v_pk_fma_f32 v[48:49], v[72:73], v[140:141], v[48:49]
	v_pk_mul_f32 v[140:141], v[154:155], v[164:165] op_sel_hi:[0,1]
	s_waitcnt vmcnt(5)
	v_pk_fma_f32 v[52:53], v[84:85], v[136:137], v[52:53]
	v_pk_mul_f32 v[136:137], v[154:155], v[166:167] op_sel_hi:[0,1]
	v_pk_mul_f32 v[134:135], v[154:155], v[134:135] op_sel_hi:[0,1]
	v_pk_fma_f32 v[42:43], v[74:75], v[150:151], v[42:43]
	v_pk_mul_f32 v[142:143], v[26:27], v[142:143]
	v_pk_mul_f32 v[140:141], v[18:19], v[140:141]
	v_pk_mul_f32 v[136:137], v[10:11], v[136:137]
	v_pk_mul_f32 v[134:135], v[12:13], v[134:135]
	v_pk_fma_f32 v[46:47], v[70:71], v[142:143], v[46:47]
	v_pk_fma_f32 v[50:51], v[82:83], v[140:141], v[50:51]
	s_waitcnt vmcnt(4)
	v_pk_fma_f32 v[38:39], v[86:87], v[136:137], v[38:39]
	v_pk_fma_f32 v[40:41], v[88:89], v[134:135], v[40:41]
	global_store_dwordx4 v[4:5], v[42:45], off sc1
	global_store_dwordx4 v[4:5], v[46:49], off offset:1024 sc1
	global_store_dwordx4 v[4:5], v[50:53], off offset:2048 sc1
	global_store_dwordx4 v[4:5], v[38:41], off offset:3072 sc1
	v_pk_mul_f32 v[4:5], v[42:43], v[42:43]
	v_pk_mul_f32 v[134:135], v[44:45], v[44:45]
	v_add_f32_e32 v4, v4, v5
	v_add_f32_e32 v4, v134, v4
	v_pk_mul_f32 v[136:137], v[46:47], v[46:47]
	v_add_f32_e32 v4, v135, v4
	v_add_f32_e32 v4, v136, v4
	v_pk_mul_f32 v[140:141], v[48:49], v[48:49]
	v_add_f32_e32 v4, v137, v4
	v_add_f32_e32 v4, v140, v4
	v_pk_mul_f32 v[142:143], v[50:51], v[50:51]
	v_add_f32_e32 v4, v141, v4
	v_add_f32_e32 v4, v142, v4
	v_pk_mul_f32 v[150:151], v[52:53], v[52:53]
	v_add_f32_e32 v4, v143, v4
	v_add_f32_e32 v4, v150, v4
	v_pk_mul_f32 v[154:155], v[38:39], v[38:39]
	v_add_f32_e32 v4, v151, v4
	v_add_f32_e32 v4, v154, v4
	v_pk_mul_f32 v[156:157], v[40:41], v[40:41]
	v_add_f32_e32 v4, v155, v4
	v_add_f32_e32 v4, v156, v4
	v_add_f32_e32 v4, v157, v4
	v_pk_add_f32 v[136:137], v[78:79], 1.0 op_sel_hi:[1,0]
	v_lshl_add_u64 v[134:135], v[126:127], 0, v[124:125]
	v_add_f32_dpp v4, v4, v4 row_ror:1 row_mask:0xf bank_mask:0xf bound_ctrl:1
	v_lshl_add_u64 v[126:127], v[126:127], 0, s[8:9]
	s_waitcnt vmcnt(6)
	v_mov_b64_e32 v[140:141], v[146:147]
	v_add_f32_dpp v4, v4, v4 row_ror:2 row_mask:0xf bank_mask:0xf bound_ctrl:1
	v_mov_b64_e32 v[142:143], v[148:149]
	v_mov_b32_e32 v150, v2
	v_add_f32_dpp v4, v4, v4 row_ror:4 row_mask:0xf bank_mask:0xf bound_ctrl:1
	s_nop 1
	v_add_f32_dpp v4, v4, v4 row_ror:8 row_mask:0xf bank_mask:0xf bound_ctrl:1
	ds_bpermute_b32 v5, v152, v4
	s_waitcnt lgkmcnt(0)
	v_add_f32_e32 v4, v4, v5
	v_mov_b32_e32 v5, v4
	s_nop 1
	v_permlane32_swap_b32 v5, v4
	s_nop 1
	s_nop 0
	v_add_f32_e32 v4, v5, v4
	v_fmamk_f32 v4, v4, 0x3a800000, v1
	v_cmp_gt_f32_e32 vcc, s91, v4
	v_mul_f32_e32 v5, 0x4b800000, v4
	s_nop 0
	v_cndmask_b32_e32 v4, v4, v5, vcc
	v_rsq_f32_e32 v4, v4
	s_nop 0
	v_mul_f32_e32 v5, 0x45800000, v4
	v_cndmask_b32_e32 v4, v4, v5, vcc
	v_pk_mul_f32 v[42:43], v[42:43], v[4:5] op_sel_hi:[1,0]
	v_pk_mul_f32 v[44:45], v[44:45], v[4:5] op_sel_hi:[1,0]
	v_pk_mul_f32 v[42:43], v[30:31], v[42:43]
	v_pk_mul_f32 v[44:45], v[32:33], v[44:45]
	v_pk_fma_f32 v[42:43], v[136:137], v[42:43], v[98:99]
	v_pk_add_f32 v[136:137], v[80:81], 1.0 op_sel_hi:[1,0]
	v_cvt_pk_bf16_f32 v42, v42, v43
	v_pk_fma_f32 v[44:45], v[136:137], v[44:45], v[100:101]
	v_pk_mul_f32 v[38:39], v[38:39], v[4:5] op_sel_hi:[1,0]
	v_cvt_pk_bf16_f32 v43, v44, v45
	v_add_co_u32_e32 v44, vcc, s0, v134
	v_pk_mul_f32 v[38:39], v[6:7], v[38:39]
	s_nop 0
	v_addc_co_u32_e32 v45, vcc, 0, v135, vcc
	global_store_dwordx2 v[44:45], v[42:43], off sc1
	v_pk_mul_f32 v[42:43], v[46:47], v[4:5] op_sel_hi:[1,0]
	v_pk_add_f32 v[46:47], v[90:91], 1.0 op_sel_hi:[1,0]
	v_pk_mul_f32 v[42:43], v[22:23], v[42:43]
	s_waitcnt vmcnt(5)
	v_mov_b64_e32 v[134:135], v[138:139]
	v_pk_fma_f32 v[42:43], v[46:47], v[42:43], v[106:107]
	v_pk_mul_f32 v[46:47], v[48:49], v[4:5] op_sel_hi:[1,0]
	v_pk_add_f32 v[48:49], v[92:93], 1.0 op_sel_hi:[1,0]
	v_pk_mul_f32 v[46:47], v[24:25], v[46:47]
	v_cvt_pk_bf16_f32 v42, v42, v43
	v_pk_fma_f32 v[46:47], v[48:49], v[46:47], v[108:109]
	v_pk_add_f32 v[48:49], v[96:97], 1.0 op_sel_hi:[1,0]
	v_cvt_pk_bf16_f32 v43, v46, v47
	global_store_dwordx2 v[44:45], v[42:43], off offset:512 sc1
	v_pk_mul_f32 v[42:43], v[50:51], v[4:5] op_sel_hi:[1,0]
	v_pk_add_f32 v[46:47], v[94:95], 1.0 op_sel_hi:[1,0]
	v_pk_mul_f32 v[42:43], v[14:15], v[42:43]
	v_mov_b64_e32 v[136:137], v[144:145]
	v_pk_fma_f32 v[42:43], v[46:47], v[42:43], v[114:115]
	v_pk_mul_f32 v[46:47], v[52:53], v[4:5] op_sel_hi:[1,0]
	v_cvt_pk_bf16_f32 v42, v42, v43
	v_pk_mul_f32 v[46:47], v[16:17], v[46:47]
	v_pk_mul_f32 v[4:5], v[40:41], v[4:5] op_sel_hi:[1,0]
	v_pk_fma_f32 v[46:47], v[48:49], v[46:47], v[116:117]
	v_pk_mul_f32 v[4:5], v[8:9], v[4:5]
	v_cvt_pk_bf16_f32 v43, v46, v47
	global_store_dwordx2 v[44:45], v[42:43], off offset:1024 sc1
	v_pk_add_f32 v[42:43], v[102:103], 1.0 op_sel_hi:[1,0]
	v_pk_add_f32 v[40:41], v[104:105], 1.0 op_sel_hi:[1,0]
	v_pk_fma_f32 v[38:39], v[42:43], v[38:39], v[110:111]
	v_pk_fma_f32 v[4:5], v[40:41], v[4:5], v[112:113]
	v_cvt_pk_bf16_f32 v38, v38, v39
	v_cvt_pk_bf16_f32 v39, v4, v5
	global_store_dwordx2 v[44:45], v[38:39], off offset:1536 sc1
	v_mov_b64_e32 v[42:43], v[54:55]
	v_mov_b64_e32 v[46:47], v[58:59]
	v_mov_b64_e32 v[50:51], v[62:63]
	v_mov_b64_e32 v[38:39], v[66:67]
	v_mov_b64_e32 v[44:45], v[56:57]
	v_mov_b64_e32 v[48:49], v[60:61]
	v_mov_b64_e32 v[52:53], v[64:65]
	v_mov_b64_e32 v[40:41], v[68:69]
	s_andn2_b64 exec, exec, s[12:13]
	s_cbranch_execz .LBB0_279

.LBB0_292:
	v_or_b32_e32 v142, 0x10000, v146
	v_add_u32_e32 v143, 0x10400, v146
	ds_read_b128 v[148:151], v142
	ds_read_b128 v[152:155], v143
	v_add_u32_e32 v142, 0x10800, v146
	v_add_u32_e32 v143, 0x10c00, v146
	ds_read_b128 v[156:159], v142
	ds_read_b128 v[160:163], v143
	s_add_u32 s14, s12, 0xfffc0080
	s_addc_u32 s15, s13, -1
	s_cmp_eq_u32 s45, 12
	s_cselect_b32 s17, s7, s15
	s_cselect_b32 s16, s41, s14
	s_cselect_b32 s15, s5, s44
	s_cselect_b32 s14, s42, s43
	v_lshl_add_u64 v[142:143], s[12:13], 0, v[138:139]
	s_add_i32 m0, s20, 0xc000
	ds_read_b128 v[164:167], v145
	ds_read_b128 v[168:171], v145 offset:1024
	ds_read_b128 v[172:175], v145 offset:2048
	ds_read_b128 v[176:179], v145 offset:3072
	ds_read_b128 v[194:197], v145 offset:4096
	ds_read_b128 v[198:201], v145 offset:5120
	ds_read_b128 v[202:205], v145 offset:6144
	ds_read_b128 v[206:209], v145 offset:7168
	global_load_lds_dwordx4 v[142:143], off
	v_lshl_add_u64 v[142:143], s[12:13], 0, v[140:141]
	s_add_i32 m0, s20, 0xe000
	s_nop 0
	global_load_lds_dwordx4 v[142:143], off
	s_waitcnt lgkmcnt(8)
	s_barrier
	s_waitcnt lgkmcnt(0)
	s_setprio 1
	s_waitcnt lgkmcnt(0)
	v_mfma_f32_16x16x32_bf16 v[128:131], v[148:151], v[164:167], v[128:131]
	v_mfma_f32_16x16x32_bf16 v[124:127], v[156:159], v[164:167], v[124:127]
	v_mfma_f32_16x16x32_bf16 v[120:123], v[148:151], v[172:175], v[120:123]
	v_mfma_f32_16x16x32_bf16 v[112:115], v[156:159], v[172:175], v[112:115]
	v_mfma_f32_16x16x32_bf16 v[104:107], v[148:151], v[194:197], v[104:107]
	v_mfma_f32_16x16x32_bf16 v[96:99], v[156:159], v[194:197], v[96:99]
	v_mfma_f32_16x16x32_bf16 v[84:87], v[148:151], v[202:205], v[84:87]
	v_mfma_f32_16x16x32_bf16 v[76:79], v[156:159], v[202:205], v[76:79]
	v_mfma_f32_16x16x32_bf16 v[128:131], v[152:155], v[168:171], v[128:131]
	v_mfma_f32_16x16x32_bf16 v[124:127], v[160:163], v[168:171], v[124:127]
	v_mfma_f32_16x16x32_bf16 v[120:123], v[152:155], v[176:179], v[120:123]
	v_mfma_f32_16x16x32_bf16 v[112:115], v[160:163], v[176:179], v[112:115]
	v_mfma_f32_16x16x32_bf16 v[104:107], v[152:155], v[198:201], v[104:107]
	v_mfma_f32_16x16x32_bf16 v[96:99], v[160:163], v[198:201], v[96:99]
	v_mfma_f32_16x16x32_bf16 v[84:87], v[152:155], v[206:209], v[84:87]
	v_mfma_f32_16x16x32_bf16 v[76:79], v[160:163], v[206:209], v[76:79]
	s_setprio 0
	s_barrier
	v_or_b32_e32 v142, 0x14000, v146
	v_add_u32_e32 v143, 0x14400, v146
	ds_read_b128 v[210:213], v142
	ds_read_b128 v[214:217], v143
	v_add_u32_e32 v142, 0x14800, v146
	v_add_u32_e32 v143, 0x14c00, v146
	s_mov_b32 m0, s21
	ds_read_b128 v[218:221], v142
	ds_read_b128 v[222:225], v143
	v_lshl_add_u64 v[142:143], s[14:15], 0, v[2:3]
	global_load_lds_dwordx4 v[142:143], off
	v_lshl_add_u64 v[240:241], s[14:15], 0, v[132:133]
	s_mov_b32 m0, s22
	s_nop 0
	global_load_lds_dwordx4 v[240:241], off
	s_barrier
	s_waitcnt lgkmcnt(0)
	s_setprio 1
	s_waitcnt lgkmcnt(0)
	v_mfma_f32_16x16x32_bf16 v[116:119], v[210:213], v[164:167], v[116:119]
	v_mfma_f32_16x16x32_bf16 v[108:111], v[218:221], v[164:167], v[108:111]
	v_mfma_f32_16x16x32_bf16 v[100:103], v[210:213], v[172:175], v[100:103]
	v_mfma_f32_16x16x32_bf16 v[92:95], v[218:221], v[172:175], v[92:95]
	v_mfma_f32_16x16x32_bf16 v[88:91], v[210:213], v[194:197], v[88:91]
	v_mfma_f32_16x16x32_bf16 v[80:83], v[218:221], v[194:197], v[80:83]
	v_mfma_f32_16x16x32_bf16 v[72:75], v[210:213], v[202:205], v[72:75]
	v_mfma_f32_16x16x32_bf16 v[68:71], v[218:221], v[202:205], v[68:71]
	v_mfma_f32_16x16x32_bf16 v[116:119], v[214:217], v[168:171], v[116:119]
	v_mfma_f32_16x16x32_bf16 v[108:111], v[222:225], v[168:171], v[108:111]
	v_mfma_f32_16x16x32_bf16 v[100:103], v[214:217], v[176:179], v[100:103]
	v_mfma_f32_16x16x32_bf16 v[92:95], v[222:225], v[176:179], v[92:95]
	v_mfma_f32_16x16x32_bf16 v[88:91], v[214:217], v[198:201], v[88:91]
	v_mfma_f32_16x16x32_bf16 v[80:83], v[222:225], v[198:201], v[80:83]
	v_mfma_f32_16x16x32_bf16 v[72:75], v[214:217], v[206:209], v[72:75]
	v_mfma_f32_16x16x32_bf16 v[68:71], v[222:225], v[206:209], v[68:71]
	s_setprio 0
	s_mov_b32 m0, s20
	v_lshl_add_u64 v[242:243], s[16:17], 0, v[136:137]
	s_barrier
	ds_read_b128 v[164:167], v145 offset:16384
	ds_read_b128 v[168:171], v145 offset:17408
	ds_read_b128 v[172:175], v145 offset:18432
	ds_read_b128 v[176:179], v145 offset:19456
	ds_read_b128 v[194:197], v145 offset:20480
	ds_read_b128 v[198:201], v145 offset:21504
	ds_read_b128 v[202:205], v145 offset:22528
	ds_read_b128 v[206:209], v145 offset:23552
	global_load_lds_dwordx4 v[242:243], off
	v_lshl_add_u64 v[244:245], s[16:17], 0, v[134:135]
	s_mov_b32 m0, s23
	s_nop 0
	global_load_lds_dwordx4 v[244:245], off
	s_barrier
	s_waitcnt lgkmcnt(0)
	s_setprio 1
	s_waitcnt lgkmcnt(0)
	v_mfma_f32_16x16x32_bf16 v[64:67], v[148:151], v[164:167], v[64:67]
	v_mfma_f32_16x16x32_bf16 v[60:63], v[156:159], v[164:167], v[60:63]
	v_mfma_f32_16x16x32_bf16 v[56:59], v[148:151], v[172:175], v[56:59]
	v_mfma_f32_16x16x32_bf16 v[48:51], v[156:159], v[172:175], v[48:51]
	v_mfma_f32_16x16x32_bf16 v[40:43], v[148:151], v[194:197], v[40:43]
	v_mfma_f32_16x16x32_bf16 v[32:35], v[156:159], v[194:197], v[32:35]
	v_mfma_f32_16x16x32_bf16 v[24:27], v[148:151], v[202:205], v[24:27]
	v_mfma_f32_16x16x32_bf16 v[16:19], v[156:159], v[202:205], v[16:19]
	v_mfma_f32_16x16x32_bf16 v[64:67], v[152:155], v[168:171], v[64:67]
	v_mfma_f32_16x16x32_bf16 v[60:63], v[160:163], v[168:171], v[60:63]
	v_mfma_f32_16x16x32_bf16 v[56:59], v[152:155], v[176:179], v[56:59]
	v_mfma_f32_16x16x32_bf16 v[48:51], v[160:163], v[176:179], v[48:51]
	v_mfma_f32_16x16x32_bf16 v[40:43], v[152:155], v[198:201], v[40:43]
	v_mfma_f32_16x16x32_bf16 v[32:35], v[160:163], v[198:201], v[32:35]
	v_mfma_f32_16x16x32_bf16 v[24:27], v[152:155], v[206:209], v[24:27]
	v_mfma_f32_16x16x32_bf16 v[16:19], v[160:163], v[206:209], v[16:19]
	s_setprio 0
	s_barrier
	s_add_u32 s46, s14, 0x40000
	s_addc_u32 s47, s15, 0
	s_mov_b32 m0, s24
	v_lshl_add_u64 v[148:149], s[46:47], 0, v[2:3]
	global_load_lds_dwordx4 v[148:149], off
	v_lshl_add_u64 v[148:149], s[46:47], 0, v[132:133]
	s_mov_b32 m0, s25
	s_nop 0
	global_load_lds_dwordx4 v[148:149], off
	s_waitcnt vmcnt(6)
	s_barrier
	s_setprio 1
	v_mfma_f32_16x16x32_bf16 v[52:55], v[210:213], v[164:167], v[52:55]
	v_mfma_f32_16x16x32_bf16 v[44:47], v[218:221], v[164:167], v[44:47]
	v_mfma_f32_16x16x32_bf16 v[36:39], v[210:213], v[172:175], v[36:39]
	v_mfma_f32_16x16x32_bf16 v[28:31], v[218:221], v[172:175], v[28:31]
	v_mfma_f32_16x16x32_bf16 v[20:23], v[210:213], v[194:197], v[20:23]
	v_mfma_f32_16x16x32_bf16 v[12:15], v[218:221], v[194:197], v[12:15]
	v_mfma_f32_16x16x32_bf16 v[8:11], v[210:213], v[202:205], v[8:11]
	v_mfma_f32_16x16x32_bf16 v[4:7], v[218:221], v[202:205], v[4:7]
	v_mfma_f32_16x16x32_bf16 v[52:55], v[214:217], v[168:171], v[52:55]
	v_mfma_f32_16x16x32_bf16 v[44:47], v[222:225], v[168:171], v[44:47]
	v_mfma_f32_16x16x32_bf16 v[36:39], v[214:217], v[176:179], v[36:39]
	v_mfma_f32_16x16x32_bf16 v[28:31], v[222:225], v[176:179], v[28:31]
	v_mfma_f32_16x16x32_bf16 v[20:23], v[214:217], v[198:201], v[20:23]
	v_mfma_f32_16x16x32_bf16 v[12:15], v[222:225], v[198:201], v[12:15]
	v_mfma_f32_16x16x32_bf16 v[8:11], v[214:217], v[206:209], v[8:11]
	v_mfma_f32_16x16x32_bf16 v[4:7], v[222:225], v[206:209], v[4:7]
	s_setprio 0
	v_or_b32_e32 v148, 0x18000, v146
	v_add_u32_e32 v152, 0x18400, v146
	v_add_u32_e32 v156, 0x18800, v146
	v_add_u32_e32 v160, 0x18c00, v146
	s_barrier
	ds_read_b128 v[148:151], v148
	ds_read_b128 v[152:155], v152
	ds_read_b128 v[156:159], v156
	ds_read_b128 v[160:163], v160
	s_add_u32 s16, s16, 0x40000
	s_addc_u32 s17, s17, 0
	s_mov_b32 m0, s26
	v_lshl_add_u64 v[210:211], s[16:17], 0, v[136:137]
	ds_read_b128 v[164:167], v145 offset:32768
	ds_read_b128 v[168:171], v145 offset:33792
	ds_read_b128 v[172:175], v145 offset:34816
	ds_read_b128 v[176:179], v145 offset:35840
	ds_read_b128 v[194:197], v145 offset:36864
	ds_read_b128 v[198:201], v145 offset:37888
	ds_read_b128 v[202:205], v145 offset:38912
	ds_read_b128 v[206:209], v145 offset:39936
	global_load_lds_dwordx4 v[210:211], off
	v_lshl_add_u64 v[210:211], s[16:17], 0, v[134:135]
	s_mov_b32 m0, s27
	s_nop 0
	global_load_lds_dwordx4 v[210:211], off
	s_waitcnt lgkmcnt(8)
	s_barrier
	s_waitcnt lgkmcnt(0)
	s_setprio 1
	s_waitcnt lgkmcnt(0)
	v_mfma_f32_16x16x32_bf16 v[128:131], v[148:151], v[164:167], v[128:131]
	v_mfma_f32_16x16x32_bf16 v[124:127], v[156:159], v[164:167], v[124:127]
	v_mfma_f32_16x16x32_bf16 v[120:123], v[148:151], v[172:175], v[120:123]
	v_mfma_f32_16x16x32_bf16 v[112:115], v[156:159], v[172:175], v[112:115]
	v_mfma_f32_16x16x32_bf16 v[104:107], v[148:151], v[194:197], v[104:107]
	v_mfma_f32_16x16x32_bf16 v[96:99], v[156:159], v[194:197], v[96:99]
	v_mfma_f32_16x16x32_bf16 v[84:87], v[148:151], v[202:205], v[84:87]
	v_mfma_f32_16x16x32_bf16 v[76:79], v[156:159], v[202:205], v[76:79]
	v_mfma_f32_16x16x32_bf16 v[128:131], v[152:155], v[168:171], v[128:131]
	v_mfma_f32_16x16x32_bf16 v[124:127], v[160:163], v[168:171], v[124:127]
	v_mfma_f32_16x16x32_bf16 v[120:123], v[152:155], v[176:179], v[120:123]
	v_mfma_f32_16x16x32_bf16 v[112:115], v[160:163], v[176:179], v[112:115]
	v_mfma_f32_16x16x32_bf16 v[104:107], v[152:155], v[198:201], v[104:107]
	v_mfma_f32_16x16x32_bf16 v[96:99], v[160:163], v[198:201], v[96:99]
	v_mfma_f32_16x16x32_bf16 v[84:87], v[152:155], v[206:209], v[84:87]
	v_mfma_f32_16x16x32_bf16 v[76:79], v[160:163], v[206:209], v[76:79]
	s_setprio 0
	s_barrier
	v_or_b32_e32 v189, 0x1c000, v146
	v_add_u32_e32 v214, 0x1c400, v146
	s_mov_b32 m0, s29
	ds_read_b128 v[210:213], v189
	ds_read_b128 v[214:217], v214
	v_add_u32_e32 v189, 0x1c800, v146
	v_add_u32_e32 v222, 0x1cc00, v146
	v_lshl_add_u64 v[142:143], v[142:143], 0, s[82:83]
	ds_read_b128 v[218:221], v189
	ds_read_b128 v[222:225], v222
	global_load_lds_dwordx4 v[142:143], off
	v_lshl_add_u64 v[142:143], v[240:241], 0, s[82:83]
	s_mov_b32 m0, s30
	s_nop 0
	global_load_lds_dwordx4 v[142:143], off
	s_barrier
	s_waitcnt lgkmcnt(0)
	s_setprio 1
	s_waitcnt lgkmcnt(0)
	v_mfma_f32_16x16x32_bf16 v[116:119], v[210:213], v[164:167], v[116:119]
	v_mfma_f32_16x16x32_bf16 v[108:111], v[218:221], v[164:167], v[108:111]
	v_mfma_f32_16x16x32_bf16 v[100:103], v[210:213], v[172:175], v[100:103]
	v_mfma_f32_16x16x32_bf16 v[92:95], v[218:221], v[172:175], v[92:95]
	v_mfma_f32_16x16x32_bf16 v[88:91], v[210:213], v[194:197], v[88:91]
	v_mfma_f32_16x16x32_bf16 v[80:83], v[218:221], v[194:197], v[80:83]
	v_mfma_f32_16x16x32_bf16 v[72:75], v[210:213], v[202:205], v[72:75]
	v_mfma_f32_16x16x32_bf16 v[68:71], v[218:221], v[202:205], v[68:71]
	v_mfma_f32_16x16x32_bf16 v[116:119], v[214:217], v[168:171], v[116:119]
	v_mfma_f32_16x16x32_bf16 v[108:111], v[222:225], v[168:171], v[108:111]
	v_mfma_f32_16x16x32_bf16 v[100:103], v[214:217], v[176:179], v[100:103]
	v_mfma_f32_16x16x32_bf16 v[92:95], v[222:225], v[176:179], v[92:95]
	v_mfma_f32_16x16x32_bf16 v[88:91], v[214:217], v[198:201], v[88:91]
	v_mfma_f32_16x16x32_bf16 v[80:83], v[222:225], v[198:201], v[80:83]
	v_mfma_f32_16x16x32_bf16 v[72:75], v[214:217], v[206:209], v[72:75]
	v_mfma_f32_16x16x32_bf16 v[68:71], v[222:225], v[206:209], v[68:71]
	s_setprio 0
	s_mov_b32 m0, s31
	v_lshl_add_u64 v[142:143], v[242:243], 0, s[82:83]
	s_barrier
	ds_read_b128 v[164:167], v145 offset:49152
	ds_read_b128 v[168:171], v145 offset:50176
	ds_read_b128 v[172:175], v145 offset:51200
	ds_read_b128 v[176:179], v145 offset:52224
	ds_read_b128 v[194:197], v145 offset:53248
	ds_read_b128 v[198:201], v145 offset:54272
	ds_read_b128 v[202:205], v145 offset:55296
	ds_read_b128 v[206:209], v145 offset:56320
	global_load_lds_dwordx4 v[142:143], off
	v_lshl_add_u64 v[142:143], v[244:245], 0, s[82:83]
	s_mov_b32 m0, s34
	s_nop 0
	global_load_lds_dwordx4 v[142:143], off
	s_barrier
	s_waitcnt lgkmcnt(0)
	s_setprio 1
	s_waitcnt lgkmcnt(0)
	v_mfma_f32_16x16x32_bf16 v[64:67], v[148:151], v[164:167], v[64:67]
	v_mfma_f32_16x16x32_bf16 v[60:63], v[156:159], v[164:167], v[60:63]
	v_mfma_f32_16x16x32_bf16 v[56:59], v[148:151], v[172:175], v[56:59]
	v_mfma_f32_16x16x32_bf16 v[48:51], v[156:159], v[172:175], v[48:51]
	v_mfma_f32_16x16x32_bf16 v[40:43], v[148:151], v[194:197], v[40:43]
	v_mfma_f32_16x16x32_bf16 v[32:35], v[156:159], v[194:197], v[32:35]
	v_mfma_f32_16x16x32_bf16 v[24:27], v[148:151], v[202:205], v[24:27]
	v_mfma_f32_16x16x32_bf16 v[16:19], v[156:159], v[202:205], v[16:19]
	v_mfma_f32_16x16x32_bf16 v[64:67], v[152:155], v[168:171], v[64:67]
	v_mfma_f32_16x16x32_bf16 v[60:63], v[160:163], v[168:171], v[60:63]
	v_mfma_f32_16x16x32_bf16 v[56:59], v[152:155], v[176:179], v[56:59]
	v_mfma_f32_16x16x32_bf16 v[48:51], v[160:163], v[176:179], v[48:51]
	v_mfma_f32_16x16x32_bf16 v[40:43], v[152:155], v[198:201], v[40:43]
	v_mfma_f32_16x16x32_bf16 v[32:35], v[160:163], v[198:201], v[32:35]
	v_mfma_f32_16x16x32_bf16 v[24:27], v[152:155], v[206:209], v[24:27]
	v_mfma_f32_16x16x32_bf16 v[16:19], v[160:163], v[206:209], v[16:19]
	s_setprio 0
	s_barrier
	s_add_u32 s14, s14, 0x40080
	s_addc_u32 s15, s15, 0
	s_mov_b32 m0, s35
	v_lshl_add_u64 v[142:143], s[14:15], 0, v[2:3]
	global_load_lds_dwordx4 v[142:143], off
	v_lshl_add_u64 v[142:143], s[14:15], 0, v[132:133]
	s_mov_b32 m0, s36
	s_nop 0
	global_load_lds_dwordx4 v[142:143], off
	s_waitcnt vmcnt(6)
	s_barrier
	s_setprio 1
	v_mfma_f32_16x16x32_bf16 v[52:55], v[210:213], v[164:167], v[52:55]
	v_mfma_f32_16x16x32_bf16 v[44:47], v[218:221], v[164:167], v[44:47]
	v_mfma_f32_16x16x32_bf16 v[36:39], v[210:213], v[172:175], v[36:39]
	v_mfma_f32_16x16x32_bf16 v[28:31], v[218:221], v[172:175], v[28:31]
	v_mfma_f32_16x16x32_bf16 v[20:23], v[210:213], v[194:197], v[20:23]
	v_mfma_f32_16x16x32_bf16 v[12:15], v[218:221], v[194:197], v[12:15]
	v_mfma_f32_16x16x32_bf16 v[8:11], v[210:213], v[202:205], v[8:11]
	v_mfma_f32_16x16x32_bf16 v[4:7], v[218:221], v[202:205], v[4:7]
	v_mfma_f32_16x16x32_bf16 v[52:55], v[214:217], v[168:171], v[52:55]
	v_mfma_f32_16x16x32_bf16 v[44:47], v[222:225], v[168:171], v[44:47]
	v_mfma_f32_16x16x32_bf16 v[36:39], v[214:217], v[176:179], v[36:39]
	v_mfma_f32_16x16x32_bf16 v[28:31], v[222:225], v[176:179], v[28:31]
	v_mfma_f32_16x16x32_bf16 v[20:23], v[214:217], v[198:201], v[20:23]
	v_mfma_f32_16x16x32_bf16 v[12:15], v[222:225], v[198:201], v[12:15]
	v_mfma_f32_16x16x32_bf16 v[8:11], v[214:217], v[206:209], v[8:11]
	v_mfma_f32_16x16x32_bf16 v[4:7], v[222:225], v[206:209], v[4:7]
	s_setprio 0
	s_add_i32 s45, s45, 2
	s_add_u32 s12, s12, 0x100
	s_addc_u32 s13, s13, 0
	s_add_u32 s43, s43, 0x100
	s_addc_u32 s44, s44, 0
	s_cmp_gt_u32 s45, 13
	s_barrier
	s_cbranch_scc0 .LBB0_292
	v_lshl_add_u32 v148, s40, 8, v144
	v_lshl_or_b32 v142, s39, 8, v147
	v_ashrrev_i32_e32 v149, 31, v148
	v_readlane_b32 s12, v253, 26
	v_ashrrev_i32_e32 v143, 31, v142
	v_lshlrev_b64 v[150:151], 11, v[148:149]
	v_readlane_b32 s13, v253, 27
	v_lshlrev_b64 v[152:153], 1, v[142:143]
	v_cvt_pk_bf16_f32 v128, v128, v129
	v_cvt_pk_bf16_f32 v129, v130, v131
	v_cvt_pk_bf16_f32 v130, v124, v125
	v_cvt_pk_bf16_f32 v131, v126, v127
	s_nop 0
	v_lshl_add_u64 v[150:151], s[12:13], 0, v[150:151]
	v_lshl_add_u64 v[142:143], v[150:151], 0, v[152:153]
	global_store_dwordx4 v[142:143], v[128:131], off sc1
	v_cvt_pk_bf16_f32 v116, v116, v117
	v_cvt_pk_bf16_f32 v117, v118, v119
	v_cvt_pk_bf16_f32 v118, v108, v109
	v_or_b32_e32 v108, 16, v148
	v_ashrrev_i32_e32 v109, 31, v108
	v_lshlrev_b64 v[108:109], 11, v[108:109]
	v_lshl_add_u64 v[108:109], s[12:13], 0, v[108:109]
	v_cvt_pk_bf16_f32 v119, v110, v111
	global_store_dwordx4 v[142:143], v[116:119], off offset:256 sc1
	s_mov_b32 s5, 0x40000
	s_mov_b32 s39, s4
	v_lshl_add_u64 v[116:117], v[108:109], 0, v[152:153]
	v_cvt_pk_bf16_f32 v108, v120, v121
	v_cvt_pk_bf16_f32 v109, v122, v123
	v_cvt_pk_bf16_f32 v110, v112, v113
	v_cvt_pk_bf16_f32 v111, v114, v115
	global_store_dwordx4 v[116:117], v[108:111], off sc1
	v_cvt_pk_bf16_f32 v100, v100, v101
	v_cvt_pk_bf16_f32 v101, v102, v103
	v_cvt_pk_bf16_f32 v102, v92, v93
	v_or_b32_e32 v92, 32, v148
	v_ashrrev_i32_e32 v93, 31, v92
	v_lshlrev_b64 v[92:93], 11, v[92:93]
	v_lshl_add_u64 v[92:93], s[12:13], 0, v[92:93]
	v_cvt_pk_bf16_f32 v103, v94, v95
	global_store_dwordx4 v[116:117], v[100:103], off offset:256 sc1
	s_mov_b32 s40, s6
	s_mov_b64 s[14:15], s[10:11]
	v_lshl_add_u64 v[100:101], v[92:93], 0, v[152:153]
	v_cvt_pk_bf16_f32 v92, v104, v105
	v_cvt_pk_bf16_f32 v93, v106, v107
	v_cvt_pk_bf16_f32 v94, v96, v97
	v_cvt_pk_bf16_f32 v95, v98, v99
	global_store_dwordx4 v[100:101], v[92:95], off sc1
	v_cvt_pk_bf16_f32 v88, v88, v89
	v_cvt_pk_bf16_f32 v89, v90, v91
	v_cvt_pk_bf16_f32 v90, v80, v81
	v_or_b32_e32 v80, 48, v148
	v_ashrrev_i32_e32 v81, 31, v80
	v_lshlrev_b64 v[80:81], 11, v[80:81]
	v_lshl_add_u64 v[80:81], s[12:13], 0, v[80:81]
	v_cvt_pk_bf16_f32 v91, v82, v83
	global_store_dwordx4 v[100:101], v[88:91], off offset:256 sc1
	s_mov_b64 s[12:13], 0x40000
	s_nop 0
	v_lshl_add_u64 v[88:89], v[80:81], 0, v[152:153]
	v_cvt_pk_bf16_f32 v80, v84, v85
	v_cvt_pk_bf16_f32 v81, v86, v87
	v_cvt_pk_bf16_f32 v82, v76, v77
	v_cvt_pk_bf16_f32 v83, v78, v79
	global_store_dwordx4 v[88:89], v[80:83], off sc1
	v_cvt_pk_bf16_f32 v72, v72, v73
	v_cvt_pk_bf16_f32 v73, v74, v75
	v_cvt_pk_bf16_f32 v74, v68, v69
	v_cvt_pk_bf16_f32 v75, v70, v71
	global_store_dwordx4 v[88:89], v[72:75], off offset:256 sc1
	v_cvt_pk_bf16_f32 v64, v64, v65
	v_cvt_pk_bf16_f32 v65, v66, v67
	v_cvt_pk_bf16_f32 v66, v60, v61
	v_add_co_u32_e32 v60, vcc, s5, v142
	v_lshl_add_u64 v[68:69], v[142:143], 0, s[12:13]
	s_nop 0
	v_addc_co_u32_e32 v61, vcc, 0, v143, vcc
	s_mov_b32 s5, 0x48000
	v_cvt_pk_bf16_f32 v67, v62, v63
	global_store_dwordx4 v[60:61], v[64:67], off sc1
	v_cvt_pk_bf16_f32 v52, v52, v53
	v_cvt_pk_bf16_f32 v53, v54, v55
	v_cvt_pk_bf16_f32 v54, v44, v45
	v_cvt_pk_bf16_f32 v55, v46, v47
	global_store_dwordx4 v[68:69], v[52:55], off offset:256 sc1
	s_mov_b64 s[12:13], 0x48000
	v_cvt_pk_bf16_f32 v44, v56, v57
	v_cvt_pk_bf16_f32 v45, v58, v59
	v_cvt_pk_bf16_f32 v46, v48, v49
	v_add_co_u32_e32 v48, vcc, s5, v142
	v_lshl_add_u64 v[52:53], v[142:143], 0, s[12:13]
	s_nop 0
	v_addc_co_u32_e32 v49, vcc, 0, v143, vcc
	s_mov_b32 s5, 0x50000
	v_cvt_pk_bf16_f32 v47, v50, v51
	global_store_dwordx4 v[48:49], v[44:47], off sc1
	v_cvt_pk_bf16_f32 v36, v36, v37
	v_cvt_pk_bf16_f32 v37, v38, v39
	v_cvt_pk_bf16_f32 v38, v28, v29
	v_cvt_pk_bf16_f32 v39, v30, v31
	global_store_dwordx4 v[52:53], v[36:39], off offset:256 sc1
	s_mov_b64 s[12:13], 0x50000
	v_cvt_pk_bf16_f32 v28, v40, v41
	v_cvt_pk_bf16_f32 v29, v42, v43
	v_cvt_pk_bf16_f32 v30, v32, v33
	v_add_co_u32_e32 v32, vcc, s5, v142
	v_lshl_add_u64 v[36:37], v[142:143], 0, s[12:13]
	s_nop 0
	v_addc_co_u32_e32 v33, vcc, 0, v143, vcc
	s_mov_b32 s5, 0x58000
	v_cvt_pk_bf16_f32 v31, v34, v35
	global_store_dwordx4 v[32:33], v[28:31], off sc1
	v_cvt_pk_bf16_f32 v20, v20, v21
	v_cvt_pk_bf16_f32 v21, v22, v23
	v_cvt_pk_bf16_f32 v22, v12, v13
	v_cvt_pk_bf16_f32 v23, v14, v15
	global_store_dwordx4 v[36:37], v[20:23], off offset:256 sc1
	v_cvt_pk_bf16_f32 v12, v24, v25
	v_cvt_pk_bf16_f32 v13, v26, v27
	v_cvt_pk_bf16_f32 v14, v16, v17
	v_add_co_u32_e32 v16, vcc, s5, v142
	s_mov_b64 s[12:13], 0x58000
	s_nop 0
	v_addc_co_u32_e32 v17, vcc, 0, v143, vcc
	v_lshl_add_u64 v[20:21], v[142:143], 0, s[12:13]
	s_and_b64 vcc, exec, s[2:3]
	s_mov_b64 s[12:13], s[8:9]
	v_cvt_pk_bf16_f32 v15, v18, v19
	global_store_dwordx4 v[16:17], v[12:15], off sc1
	v_cvt_pk_bf16_f32 v8, v8, v9
	v_cvt_pk_bf16_f32 v9, v10, v11
	v_cvt_pk_bf16_f32 v10, v4, v5
	v_cvt_pk_bf16_f32 v11, v6, v7
	global_store_dwordx4 v[20:21], v[8:11], off offset:256 sc1
	s_cbranch_vccz .LBB0_285
	s_waitcnt vmcnt(0)
	s_cmpk_gt_u32 s0, 0xff
	v_readlane_b32 s34, v251, 48
	s_cbranch_scc1 .LBB0_296
	s_barrier

.LBB0_628:
	s_or_b64 exec, exec, s[18:19]
	v_lshlrev_b32_e32 v4, 16, v82
	v_and_b32_e32 v5, 0xffff0000, v82
	v_lshlrev_b32_e32 v104, 16, v80
	v_and_b32_e32 v105, 0xffff0000, v80
	v_and_b32_e32 v111, 0xffff0000, v78
	v_and_b32_e32 v113, 0xffff0000, v76
	v_pk_mul_f32 v[100:101], v[4:5], v[4:5]
	v_lshlrev_b32_e32 v82, 16, v83
	v_and_b32_e32 v83, 0xffff0000, v83
	v_pk_mul_f32 v[106:107], v[104:105], v[104:105]
	v_lshlrev_b32_e32 v80, 16, v81
	v_and_b32_e32 v81, 0xffff0000, v81
	v_lshlrev_b32_e32 v110, 16, v78
	v_lshlrev_b32_e32 v112, 16, v76
	v_mov_b32_e32 v116, v113
	v_mov_b32_e32 v117, v111
	v_pk_mul_f32 v[102:103], v[82:83], v[82:83]
	v_pk_mul_f32 v[108:109], v[80:81], v[80:81]
	v_lshlrev_b32_e32 v78, 16, v79
	v_lshlrev_b32_e32 v76, 16, v77
	v_mov_b32_e32 v114, v112
	v_mov_b32_e32 v115, v110
	v_pk_mul_f32 v[116:117], v[116:117], v[116:117]
	v_add_f32_e32 v100, v100, v101
	v_add_f32_e32 v101, v106, v107
	v_and_b32_e32 v79, 0xffff0000, v79
	v_and_b32_e32 v77, 0xffff0000, v77
	v_pk_fma_f32 v[114:115], v[114:115], v[114:115], v[116:117]
	v_mov_b32_e32 v116, v76
	v_mov_b32_e32 v117, v78
	v_add_f32_e32 v100, v102, v100
	v_add_f32_e32 v101, v108, v101
	v_mov_b32_e32 v118, v77
	v_mov_b32_e32 v119, v79
	v_pk_fma_f32 v[114:115], v[116:117], v[116:117], v[114:115]
	v_add_f32_e32 v100, v103, v100
	v_add_f32_e32 v101, v109, v101
	v_pk_fma_f32 v[114:115], v[118:119], v[118:119], v[114:115]
	v_add_f32_e32 v100, v101, v100
	v_add_f32_e32 v100, v115, v100
	v_add_f32_e32 v100, v114, v100
	s_and_b64 s[2:3], exec, vcc
	v_lshl_add_u64 v[84:85], v[86:87], 0, v[70:71]
	v_add_f32_dpp v100, v100, v100 row_ror:1 row_mask:0xf bank_mask:0xf bound_ctrl:1
	s_or_b64 s[16:17], s[2:3], s[16:17]
	v_lshl_add_u64 v[74:75], v[74:75], 0, s[12:13]
	v_add_f32_dpp v100, v100, v100 row_ror:2 row_mask:0xf bank_mask:0xf bound_ctrl:1
	v_lshl_add_u64 v[86:87], v[86:87], 0, s[12:13]
	v_lshl_add_u64 v[88:89], v[88:89], 0, s[14:15]
	v_add_f32_dpp v100, v100, v100 row_ror:4 row_mask:0xf bank_mask:0xf bound_ctrl:1
	s_nop 1
	v_add_f32_dpp v100, v100, v100 row_ror:8 row_mask:0xf bank_mask:0xf bound_ctrl:1
	ds_bpermute_b32 v101, v98, v100
	s_waitcnt lgkmcnt(0)
	v_add_f32_e32 v100, v100, v101
	v_mov_b32_e32 v101, v100
	s_nop 1
	v_permlane32_swap_b32 v100, v101
	s_nop 1
	s_nop 0
	v_add_f32_e32 v100, v100, v101
	v_fmamk_f32 v100, v100, 0x3a800000, v1
	v_cmp_gt_f32_e32 vcc, s91, v100
	v_mul_f32_e32 v101, 0x4b800000, v100
	s_nop 0
	v_cndmask_b32_e32 v100, v100, v101, vcc
	v_rsq_f32_e32 v100, v100
	s_nop 0
	v_mul_f32_e32 v101, 0x45800000, v100
	v_cndmask_b32_e32 v100, v100, v101, vcc
	v_pk_mul_f32 v[4:5], v[100:101], v[4:5] op_sel_hi:[0,1]
	v_pk_mul_f32 v[4:5], v[34:35], v[4:5]
	s_waitcnt vmcnt(3)
	v_pk_fma_f32 v[10:11], v[66:67], v[4:5], v[10:11]
	v_pk_mul_f32 v[4:5], v[100:101], v[82:83] op_sel_hi:[0,1]
	v_pk_mul_f32 v[4:5], v[36:37], v[4:5]
	v_mov_b64_e32 v[82:83], v[96:97]
	v_pk_fma_f32 v[12:13], v[68:69], v[4:5], v[12:13]
	v_pk_mul_f32 v[4:5], v[100:101], v[104:105] op_sel_hi:[0,1]
	v_pk_mul_f32 v[4:5], v[30:31], v[4:5]
	s_waitcnt vmcnt(2)
	v_pk_fma_f32 v[14:15], v[62:63], v[4:5], v[14:15]
	v_pk_mul_f32 v[4:5], v[100:101], v[80:81] op_sel_hi:[0,1]
	v_pk_mul_f32 v[4:5], v[32:33], v[4:5]
	v_mov_b64_e32 v[80:81], v[94:95]
	v_pk_fma_f32 v[16:17], v[64:65], v[4:5], v[16:17]
	v_pk_mul_f32 v[4:5], v[100:101], v[110:111] op_sel_hi:[0,1]
	v_pk_mul_f32 v[4:5], v[26:27], v[4:5]
	s_waitcnt vmcnt(1)
	v_pk_fma_f32 v[18:19], v[58:59], v[4:5], v[18:19]
	v_pk_mul_f32 v[4:5], v[100:101], v[78:79] op_sel_hi:[0,1]
	v_pk_mul_f32 v[4:5], v[28:29], v[4:5]
	v_mov_b64_e32 v[78:79], v[92:93]
	v_pk_fma_f32 v[20:21], v[60:61], v[4:5], v[20:21]
	v_pk_mul_f32 v[4:5], v[100:101], v[112:113] op_sel_hi:[0,1]
	v_pk_mul_f32 v[4:5], v[22:23], v[4:5]
	s_waitcnt vmcnt(0)
	v_pk_fma_f32 v[4:5], v[54:55], v[4:5], v[6:7]
	v_pk_mul_f32 v[6:7], v[100:101], v[76:77] op_sel_hi:[0,1]
	v_pk_mul_f32 v[6:7], v[24:25], v[6:7]
	v_mov_b64_e32 v[76:77], v[90:91]
	v_pk_fma_f32 v[6:7], v[56:57], v[6:7], v[8:9]
	global_store_dwordx4 v[84:85], v[10:13], off sc1
	global_store_dwordx4 v[84:85], v[14:17], off offset:1024 sc1
	global_store_dwordx4 v[84:85], v[18:21], off offset:2048 sc1
	global_store_dwordx4 v[84:85], v[4:7], off offset:3072 sc1
	v_mov_b64_e32 v[10:11], v[38:39]
	v_mov_b64_e32 v[14:15], v[42:43]
	v_mov_b64_e32 v[18:19], v[46:47]
	v_mov_b64_e32 v[6:7], v[50:51]
	v_mov_b64_e32 v[12:13], v[40:41]
	v_mov_b64_e32 v[16:17], v[44:45]
	v_mov_b64_e32 v[20:21], v[48:49]
	v_mov_b64_e32 v[8:9], v[52:53]
	v_mov_b32_e32 v84, v2
	s_andn2_b64 exec, exec, s[16:17]
	s_cbranch_execz .LBB0_633

.LBB0_641:
	s_or_b64 exec, exec, s[16:17]
	v_lshlrev_b32_e32 v154, 16, v146
	v_and_b32_e32 v155, 0xffff0000, v146
	v_lshlrev_b32_e32 v160, 16, v144
	v_and_b32_e32 v161, 0xffff0000, v144
	v_and_b32_e32 v167, 0xffff0000, v142
	v_and_b32_e32 v169, 0xffff0000, v140
	v_pk_mul_f32 v[156:157], v[154:155], v[154:155]
	v_lshlrev_b32_e32 v146, 16, v147
	v_and_b32_e32 v147, 0xffff0000, v147
	v_pk_mul_f32 v[162:163], v[160:161], v[160:161]
	v_lshlrev_b32_e32 v144, 16, v145
	v_and_b32_e32 v145, 0xffff0000, v145
	v_lshlrev_b32_e32 v166, 16, v142
	v_lshlrev_b32_e32 v168, 16, v140
	v_mov_b32_e32 v172, v169
	v_mov_b32_e32 v173, v167
	v_pk_mul_f32 v[158:159], v[146:147], v[146:147]
	v_pk_mul_f32 v[164:165], v[144:145], v[144:145]
	v_lshlrev_b32_e32 v142, 16, v143
	v_lshlrev_b32_e32 v140, 16, v141
	v_mov_b32_e32 v170, v168
	v_mov_b32_e32 v171, v166
	v_pk_mul_f32 v[172:173], v[172:173], v[172:173]
	v_add_f32_e32 v148, v156, v157
	v_add_f32_e32 v151, v162, v163
	v_and_b32_e32 v143, 0xffff0000, v143
	v_and_b32_e32 v141, 0xffff0000, v141
	v_pk_fma_f32 v[170:171], v[170:171], v[170:171], v[172:173]
	v_mov_b32_e32 v172, v140
	v_mov_b32_e32 v173, v142
	v_add_f32_e32 v148, v158, v148
	v_add_f32_e32 v151, v164, v151
	v_mov_b32_e32 v174, v141
	v_mov_b32_e32 v175, v143
	v_pk_fma_f32 v[170:171], v[172:173], v[172:173], v[170:171]
	v_add_f32_e32 v148, v159, v148
	v_add_f32_e32 v151, v165, v151
	v_pk_fma_f32 v[170:171], v[174:175], v[174:175], v[170:171]
	v_add_f32_e32 v148, v151, v148
	v_add_f32_e32 v148, v171, v148
	v_add_f32_e32 v148, v170, v148
	v_lshl_add_u64 v[152:153], v[128:129], 0, v[120:121]
	s_mov_b32 s0, 0x6198000
	v_add_f32_dpp v148, v148, v148 row_ror:1 row_mask:0xf bank_mask:0xf bound_ctrl:1
	s_and_b64 s[2:3], exec, s[2:3]
	s_or_b64 s[6:7], s[2:3], s[6:7]
	v_add_f32_dpp v148, v148, v148 row_ror:2 row_mask:0xf bank_mask:0xf bound_ctrl:1
	v_lshl_add_u64 v[4:5], v[4:5], 0, s[14:15]
	v_lshl_add_u64 v[128:129], v[128:129], 0, s[14:15]
	v_add_f32_dpp v148, v148, v148 row_ror:4 row_mask:0xf bank_mask:0xf bound_ctrl:1
	v_lshl_add_u64 v[138:139], v[138:139], 0, s[12:13]
	s_nop 0
	v_add_f32_dpp v148, v148, v148 row_ror:8 row_mask:0xf bank_mask:0xf bound_ctrl:1
	ds_bpermute_b32 v151, v149, v148
	s_waitcnt lgkmcnt(0)
	v_add_f32_e32 v148, v148, v151
	v_mov_b32_e32 v151, v148
	s_nop 1
	v_permlane32_swap_b32 v151, v148
	s_nop 1
	s_nop 0
	v_add_f32_e32 v148, v151, v148
	v_fmamk_f32 v148, v148, 0x3a800000, v1
	v_cmp_gt_f32_e32 vcc, s91, v148
	v_mul_f32_e32 v151, 0x4b800000, v148
	s_nop 0
	v_cndmask_b32_e32 v148, v148, v151, vcc
	v_rsq_f32_e32 v148, v148
	s_nop 0
	v_mul_f32_e32 v151, 0x45800000, v148
	v_cndmask_b32_e32 v148, v148, v151, vcc
	v_pk_mul_f32 v[154:155], v[148:149], v[154:155] op_sel_hi:[0,1]
	v_pk_mul_f32 v[142:143], v[148:149], v[142:143] op_sel_hi:[0,1]
	v_pk_mul_f32 v[154:155], v[18:19], v[154:155]
	v_pk_mul_f32 v[146:147], v[148:149], v[146:147] op_sel_hi:[0,1]
	v_pk_mul_f32 v[142:143], v[12:13], v[142:143]
	v_pk_mul_f32 v[140:141], v[148:149], v[140:141] op_sel_hi:[0,1]
	s_waitcnt vmcnt(11)
	v_pk_fma_f32 v[58:59], v[70:71], v[154:155], v[58:59]
	v_pk_mul_f32 v[146:147], v[20:21], v[146:147]
	v_pk_mul_f32 v[144:145], v[148:149], v[144:145] op_sel_hi:[0,1]
	s_waitcnt vmcnt(5)
	v_pk_fma_f32 v[68:69], v[80:81], v[142:143], v[68:69]
	v_pk_mul_f32 v[142:143], v[148:149], v[168:169] op_sel_hi:[0,1]
	v_pk_mul_f32 v[140:141], v[8:9], v[140:141]
	v_pk_fma_f32 v[60:61], v[72:73], v[146:147], v[60:61]
	v_pk_mul_f32 v[146:147], v[148:149], v[160:161] op_sel_hi:[0,1]
	v_pk_mul_f32 v[144:145], v[16:17], v[144:145]
	v_pk_mul_f32 v[142:143], v[6:7], v[142:143]
	s_waitcnt vmcnt(4)
	v_pk_fma_f32 v[56:57], v[84:85], v[140:141], v[56:57]
	v_pk_mul_f32 v[140:141], v[58:59], v[58:59]
	v_pk_mul_f32 v[146:147], v[14:15], v[146:147]
	v_pk_fma_f32 v[64:65], v[76:77], v[144:145], v[64:65]
	v_pk_mul_f32 v[144:145], v[148:149], v[166:167] op_sel_hi:[0,1]
	v_pk_fma_f32 v[54:55], v[82:83], v[142:143], v[54:55]
	v_pk_mul_f32 v[142:143], v[60:61], v[60:61]
	v_add_f32_e32 v140, v140, v141
	v_pk_fma_f32 v[62:63], v[74:75], v[146:147], v[62:63]
	v_pk_mul_f32 v[144:145], v[10:11], v[144:145]
	v_add_f32_e32 v140, v142, v140
	v_pk_fma_f32 v[66:67], v[78:79], v[144:145], v[66:67]
	v_pk_mul_f32 v[144:145], v[62:63], v[62:63]
	v_add_f32_e32 v140, v143, v140
	v_add_f32_e32 v140, v144, v140
	v_pk_mul_f32 v[146:147], v[64:65], v[64:65]
	v_add_f32_e32 v140, v145, v140
	v_add_f32_e32 v140, v146, v140
	global_store_dwordx4 v[152:153], v[58:61], off sc1
	global_store_dwordx4 v[152:153], v[62:65], off offset:1024 sc1
	global_store_dwordx4 v[152:153], v[66:69], off offset:2048 sc1
	global_store_dwordx4 v[152:153], v[54:57], off offset:3072 sc1
	v_pk_mul_f32 v[152:153], v[66:67], v[66:67]
	v_add_f32_e32 v140, v147, v140
	v_add_f32_e32 v140, v152, v140
	v_pk_mul_f32 v[154:155], v[68:69], v[68:69]
	v_add_f32_e32 v140, v153, v140
	v_add_f32_e32 v140, v154, v140
	v_pk_mul_f32 v[156:157], v[54:55], v[54:55]
	v_add_f32_e32 v140, v155, v140
	v_add_f32_e32 v140, v156, v140
	v_pk_mul_f32 v[158:159], v[56:57], v[56:57]
	v_add_f32_e32 v140, v157, v140
	v_add_f32_e32 v140, v158, v140
	v_add_f32_e32 v140, v159, v140
	s_waitcnt vmcnt(7)
	v_pk_add_f32 v[144:145], v[106:107], 1.0 op_sel_hi:[1,0]
	v_lshl_add_u64 v[142:143], v[126:127], 0, v[122:123]
	v_add_f32_dpp v140, v140, v140 row_ror:1 row_mask:0xf bank_mask:0xf bound_ctrl:1
	v_lshl_add_u64 v[126:127], v[126:127], 0, s[12:13]
	v_mov_b64_e32 v[146:147], v[136:137]
	v_add_f32_dpp v140, v140, v140 row_ror:2 row_mask:0xf bank_mask:0xf bound_ctrl:1
	v_mov_b32_e32 v148, v2
	s_nop 0
	v_add_f32_dpp v140, v140, v140 row_ror:4 row_mask:0xf bank_mask:0xf bound_ctrl:1
	s_nop 1
	v_add_f32_dpp v140, v140, v140 row_ror:8 row_mask:0xf bank_mask:0xf bound_ctrl:1
	ds_bpermute_b32 v141, v149, v140
	s_waitcnt lgkmcnt(0)
	v_add_f32_e32 v140, v140, v141
	v_mov_b32_e32 v141, v140
	s_nop 1
	v_permlane32_swap_b32 v141, v140
	s_nop 1
	s_nop 0
	v_add_f32_e32 v140, v141, v140
	v_fmamk_f32 v140, v140, 0x3a800000, v1
	v_cmp_gt_f32_e32 vcc, s91, v140
	v_mul_f32_e32 v141, 0x4b800000, v140
	s_nop 0
	v_cndmask_b32_e32 v140, v140, v141, vcc
	v_rsq_f32_e32 v140, v140
	s_nop 0
	v_mul_f32_e32 v141, 0x45800000, v140
	v_cndmask_b32_e32 v140, v140, v141, vcc
	v_pk_mul_f32 v[58:59], v[58:59], v[140:141] op_sel_hi:[1,0]
	v_pk_mul_f32 v[60:61], v[60:61], v[140:141] op_sel_hi:[1,0]
	s_waitcnt vmcnt(4)
	v_pk_mul_f32 v[58:59], v[34:35], v[58:59]
	v_pk_mul_f32 v[60:61], v[36:37], v[60:61]
	v_pk_fma_f32 v[58:59], v[144:145], v[58:59], v[94:95]
	v_pk_add_f32 v[144:145], v[108:109], 1.0 op_sel_hi:[1,0]
	v_cvt_pk_bf16_f32 v58, v58, v59
	v_pk_fma_f32 v[60:61], v[144:145], v[60:61], v[96:97]
	v_pk_mul_f32 v[54:55], v[54:55], v[140:141] op_sel_hi:[1,0]
	v_cvt_pk_bf16_f32 v59, v60, v61
	v_add_co_u32_e32 v60, vcc, s0, v142
	v_pk_mul_f32 v[54:55], v[22:23], v[54:55]
	s_nop 0
	v_addc_co_u32_e32 v61, vcc, 0, v143, vcc
	global_store_dwordx2 v[60:61], v[58:59], off sc1
	v_pk_mul_f32 v[58:59], v[62:63], v[140:141] op_sel_hi:[1,0]
	v_pk_add_f32 v[62:63], v[86:87], 1.0 op_sel_hi:[1,0]
	v_pk_mul_f32 v[58:59], v[30:31], v[58:59]
	v_pk_mul_f32 v[56:57], v[56:57], v[140:141] op_sel_hi:[1,0]
	v_pk_fma_f32 v[58:59], v[62:63], v[58:59], v[98:99]
	v_pk_mul_f32 v[62:63], v[64:65], v[140:141] op_sel_hi:[1,0]
	v_pk_add_f32 v[64:65], v[88:89], 1.0 op_sel_hi:[1,0]
	v_pk_mul_f32 v[62:63], v[32:33], v[62:63]
	v_cvt_pk_bf16_f32 v58, v58, v59
	v_pk_fma_f32 v[62:63], v[64:65], v[62:63], v[100:101]
	v_pk_add_f32 v[64:65], v[92:93], 1.0 op_sel_hi:[1,0]
	v_cvt_pk_bf16_f32 v59, v62, v63
	global_store_dwordx2 v[60:61], v[58:59], off offset:512 sc1
	v_pk_mul_f32 v[58:59], v[66:67], v[140:141] op_sel_hi:[1,0]
	v_pk_add_f32 v[62:63], v[90:91], 1.0 op_sel_hi:[1,0]
	v_pk_mul_f32 v[58:59], v[26:27], v[58:59]
	v_pk_mul_f32 v[56:57], v[24:25], v[56:57]
	v_pk_fma_f32 v[58:59], v[62:63], v[58:59], v[114:115]
	v_pk_mul_f32 v[62:63], v[68:69], v[140:141] op_sel_hi:[1,0]
	v_cvt_pk_bf16_f32 v58, v58, v59
	v_pk_mul_f32 v[62:63], v[28:29], v[62:63]
	v_mov_b64_e32 v[68:69], v[48:49]
	v_pk_fma_f32 v[62:63], v[64:65], v[62:63], v[116:117]
	v_mov_b64_e32 v[140:141], v[130:131]
	v_cvt_pk_bf16_f32 v59, v62, v63
	global_store_dwordx2 v[60:61], v[58:59], off offset:1024 sc1
	v_pk_add_f32 v[58:59], v[102:103], 1.0 op_sel_hi:[1,0]
	v_mov_b64_e32 v[64:65], v[44:45]
	v_pk_fma_f32 v[54:55], v[58:59], v[54:55], v[110:111]
	v_pk_add_f32 v[58:59], v[104:105], 1.0 op_sel_hi:[1,0]
	v_cvt_pk_bf16_f32 v54, v54, v55
	v_pk_fma_f32 v[56:57], v[58:59], v[56:57], v[112:113]
	v_mov_b64_e32 v[142:143], v[132:133]
	v_cvt_pk_bf16_f32 v55, v56, v57
	global_store_dwordx2 v[60:61], v[54:55], off offset:1536 sc1
	v_mov_b64_e32 v[60:61], v[40:41]
	v_mov_b64_e32 v[56:57], v[52:53]
	v_mov_b64_e32 v[144:145], v[134:135]
	v_mov_b64_e32 v[58:59], v[38:39]
	v_mov_b64_e32 v[62:63], v[42:43]
	v_mov_b64_e32 v[66:67], v[46:47]
	v_mov_b64_e32 v[54:55], v[50:51]
	s_andn2_b64 exec, exec, s[6:7]
	s_cbranch_execz .LBB0_826

.LBB0_655:
	v_or_b32_e32 v142, 0x10000, v148
	v_add_u32_e32 v150, 0x10400, v148
	v_add_u32_e32 v154, 0x10800, v148
	v_add_u32_e32 v158, 0x10c00, v148
	ds_read_b128 v[142:145], v142
	ds_read_b128 v[150:153], v150
	ds_read_b128 v[154:157], v154
	ds_read_b128 v[158:161], v158
	s_add_u32 s14, s12, 0xfffc0080
	s_addc_u32 s15, s13, -1
	s_cmp_eq_u32 s45, 12
	s_cselect_b32 s17, s7, s15
	s_cselect_b32 s16, s41, s14
	s_cselect_b32 s15, s5, s44
	s_cselect_b32 s14, s42, s43
	v_lshl_add_u64 v[178:179], s[12:13], 0, v[138:139]
	s_add_i32 m0, s20, 0xc000
	ds_read_b128 v[162:165], v147
	ds_read_b128 v[166:169], v147 offset:1024
	ds_read_b128 v[170:173], v147 offset:2048
	ds_read_b128 v[174:177], v147 offset:3072
	ds_read_b128 v[194:197], v147 offset:4096
	ds_read_b128 v[198:201], v147 offset:5120
	ds_read_b128 v[202:205], v147 offset:6144
	ds_read_b128 v[206:209], v147 offset:7168
	global_load_lds_dwordx4 v[178:179], off
	v_lshl_add_u64 v[178:179], s[12:13], 0, v[140:141]
	s_add_i32 m0, s20, 0xe000
	s_nop 0
	global_load_lds_dwordx4 v[178:179], off
	s_waitcnt lgkmcnt(8)
	s_barrier
	s_waitcnt lgkmcnt(0)
	s_setprio 1
	s_waitcnt lgkmcnt(0)
	v_mfma_f32_16x16x32_bf16 v[128:131], v[142:145], v[162:165], v[128:131]
	v_mfma_f32_16x16x32_bf16 v[124:127], v[154:157], v[162:165], v[124:127]
	v_mfma_f32_16x16x32_bf16 v[120:123], v[142:145], v[170:173], v[120:123]
	v_mfma_f32_16x16x32_bf16 v[112:115], v[154:157], v[170:173], v[112:115]
	v_mfma_f32_16x16x32_bf16 v[104:107], v[142:145], v[194:197], v[104:107]
	v_mfma_f32_16x16x32_bf16 v[96:99], v[154:157], v[194:197], v[96:99]
	v_mfma_f32_16x16x32_bf16 v[88:91], v[142:145], v[202:205], v[88:91]
	v_mfma_f32_16x16x32_bf16 v[80:83], v[154:157], v[202:205], v[80:83]
	v_mfma_f32_16x16x32_bf16 v[128:131], v[150:153], v[166:169], v[128:131]
	v_mfma_f32_16x16x32_bf16 v[124:127], v[158:161], v[166:169], v[124:127]
	v_mfma_f32_16x16x32_bf16 v[120:123], v[150:153], v[174:177], v[120:123]
	v_mfma_f32_16x16x32_bf16 v[112:115], v[158:161], v[174:177], v[112:115]
	v_mfma_f32_16x16x32_bf16 v[104:107], v[150:153], v[198:201], v[104:107]
	v_mfma_f32_16x16x32_bf16 v[96:99], v[158:161], v[198:201], v[96:99]
	v_mfma_f32_16x16x32_bf16 v[88:91], v[150:153], v[206:209], v[88:91]
	v_mfma_f32_16x16x32_bf16 v[80:83], v[158:161], v[206:209], v[80:83]
	s_setprio 0
	s_barrier
	v_or_b32_e32 v178, 0x14000, v148
	v_add_u32_e32 v179, 0x14400, v148
	ds_read_b128 v[210:213], v178
	ds_read_b128 v[214:217], v179
	v_add_u32_e32 v178, 0x14800, v148
	v_add_u32_e32 v179, 0x14c00, v148
	s_mov_b32 m0, s21
	ds_read_b128 v[218:221], v178
	ds_read_b128 v[222:225], v179
	v_lshl_add_u64 v[178:179], s[14:15], 0, v[2:3]
	global_load_lds_dwordx4 v[178:179], off
	v_lshl_add_u64 v[240:241], s[14:15], 0, v[132:133]
	s_mov_b32 m0, s22
	s_nop 0
	global_load_lds_dwordx4 v[240:241], off
	s_barrier
	s_waitcnt lgkmcnt(0)
	s_setprio 1
	s_waitcnt lgkmcnt(0)
	v_mfma_f32_16x16x32_bf16 v[116:119], v[210:213], v[162:165], v[116:119]
	v_mfma_f32_16x16x32_bf16 v[108:111], v[218:221], v[162:165], v[108:111]
	v_mfma_f32_16x16x32_bf16 v[100:103], v[210:213], v[170:173], v[100:103]
	v_mfma_f32_16x16x32_bf16 v[92:95], v[218:221], v[170:173], v[92:95]
	v_mfma_f32_16x16x32_bf16 v[84:87], v[210:213], v[194:197], v[84:87]
	v_mfma_f32_16x16x32_bf16 v[76:79], v[218:221], v[194:197], v[76:79]
	v_mfma_f32_16x16x32_bf16 v[72:75], v[210:213], v[202:205], v[72:75]
	v_mfma_f32_16x16x32_bf16 v[68:71], v[218:221], v[202:205], v[68:71]
	v_mfma_f32_16x16x32_bf16 v[116:119], v[214:217], v[166:169], v[116:119]
	v_mfma_f32_16x16x32_bf16 v[108:111], v[222:225], v[166:169], v[108:111]
	v_mfma_f32_16x16x32_bf16 v[100:103], v[214:217], v[174:177], v[100:103]
	v_mfma_f32_16x16x32_bf16 v[92:95], v[222:225], v[174:177], v[92:95]
	v_mfma_f32_16x16x32_bf16 v[84:87], v[214:217], v[198:201], v[84:87]
	v_mfma_f32_16x16x32_bf16 v[76:79], v[222:225], v[198:201], v[76:79]
	v_mfma_f32_16x16x32_bf16 v[72:75], v[214:217], v[206:209], v[72:75]
	v_mfma_f32_16x16x32_bf16 v[68:71], v[222:225], v[206:209], v[68:71]
	s_setprio 0
	s_mov_b32 m0, s20
	v_lshl_add_u64 v[242:243], s[16:17], 0, v[136:137]
	s_barrier
	ds_read_b128 v[162:165], v147 offset:16384
	ds_read_b128 v[166:169], v147 offset:17408
	ds_read_b128 v[170:173], v147 offset:18432
	ds_read_b128 v[174:177], v147 offset:19456
	ds_read_b128 v[194:197], v147 offset:20480
	ds_read_b128 v[198:201], v147 offset:21504
	ds_read_b128 v[202:205], v147 offset:22528
	ds_read_b128 v[206:209], v147 offset:23552
	global_load_lds_dwordx4 v[242:243], off
	v_lshl_add_u64 v[244:245], s[16:17], 0, v[134:135]
	s_mov_b32 m0, s23
	s_nop 0
	global_load_lds_dwordx4 v[244:245], off
	s_barrier
	s_waitcnt lgkmcnt(0)
	s_setprio 1
	s_waitcnt lgkmcnt(0)
	v_mfma_f32_16x16x32_bf16 v[64:67], v[142:145], v[162:165], v[64:67]
	v_mfma_f32_16x16x32_bf16 v[60:63], v[154:157], v[162:165], v[60:63]
	v_mfma_f32_16x16x32_bf16 v[56:59], v[142:145], v[170:173], v[56:59]
	v_mfma_f32_16x16x32_bf16 v[48:51], v[154:157], v[170:173], v[48:51]
	v_mfma_f32_16x16x32_bf16 v[40:43], v[142:145], v[194:197], v[40:43]
	v_mfma_f32_16x16x32_bf16 v[32:35], v[154:157], v[194:197], v[32:35]
	v_mfma_f32_16x16x32_bf16 v[24:27], v[142:145], v[202:205], v[24:27]
	v_mfma_f32_16x16x32_bf16 v[16:19], v[154:157], v[202:205], v[16:19]
	v_mfma_f32_16x16x32_bf16 v[64:67], v[150:153], v[166:169], v[64:67]
	v_mfma_f32_16x16x32_bf16 v[60:63], v[158:161], v[166:169], v[60:63]
	v_mfma_f32_16x16x32_bf16 v[56:59], v[150:153], v[174:177], v[56:59]
	v_mfma_f32_16x16x32_bf16 v[48:51], v[158:161], v[174:177], v[48:51]
	v_mfma_f32_16x16x32_bf16 v[40:43], v[150:153], v[198:201], v[40:43]
	v_mfma_f32_16x16x32_bf16 v[32:35], v[158:161], v[198:201], v[32:35]
	v_mfma_f32_16x16x32_bf16 v[24:27], v[150:153], v[206:209], v[24:27]
	v_mfma_f32_16x16x32_bf16 v[16:19], v[158:161], v[206:209], v[16:19]
	s_setprio 0
	s_barrier
	s_add_u32 s46, s14, 0x40000
	s_addc_u32 s47, s15, 0
	s_mov_b32 m0, s24
	v_lshl_add_u64 v[142:143], s[46:47], 0, v[2:3]
	global_load_lds_dwordx4 v[142:143], off
	v_lshl_add_u64 v[142:143], s[46:47], 0, v[132:133]
	s_mov_b32 m0, s25
	s_nop 0
	global_load_lds_dwordx4 v[142:143], off
	s_waitcnt vmcnt(6)
	s_barrier
	s_setprio 1
	v_mfma_f32_16x16x32_bf16 v[52:55], v[210:213], v[162:165], v[52:55]
	v_mfma_f32_16x16x32_bf16 v[44:47], v[218:221], v[162:165], v[44:47]
	v_mfma_f32_16x16x32_bf16 v[36:39], v[210:213], v[170:173], v[36:39]
	v_mfma_f32_16x16x32_bf16 v[28:31], v[218:221], v[170:173], v[28:31]
	v_mfma_f32_16x16x32_bf16 v[20:23], v[210:213], v[194:197], v[20:23]
	v_mfma_f32_16x16x32_bf16 v[12:15], v[218:221], v[194:197], v[12:15]
	v_mfma_f32_16x16x32_bf16 v[8:11], v[210:213], v[202:205], v[8:11]
	v_mfma_f32_16x16x32_bf16 v[4:7], v[218:221], v[202:205], v[4:7]
	v_mfma_f32_16x16x32_bf16 v[52:55], v[214:217], v[166:169], v[52:55]
	v_mfma_f32_16x16x32_bf16 v[44:47], v[222:225], v[166:169], v[44:47]
	v_mfma_f32_16x16x32_bf16 v[36:39], v[214:217], v[174:177], v[36:39]
	v_mfma_f32_16x16x32_bf16 v[28:31], v[222:225], v[174:177], v[28:31]
	v_mfma_f32_16x16x32_bf16 v[20:23], v[214:217], v[198:201], v[20:23]
	v_mfma_f32_16x16x32_bf16 v[12:15], v[222:225], v[198:201], v[12:15]
	v_mfma_f32_16x16x32_bf16 v[8:11], v[214:217], v[206:209], v[8:11]
	v_mfma_f32_16x16x32_bf16 v[4:7], v[222:225], v[206:209], v[4:7]
	s_setprio 0
	v_or_b32_e32 v142, 0x18000, v148
	v_add_u32_e32 v150, 0x18400, v148
	v_add_u32_e32 v154, 0x18800, v148
	v_add_u32_e32 v158, 0x18c00, v148
	s_barrier
	ds_read_b128 v[142:145], v142
	ds_read_b128 v[150:153], v150
	ds_read_b128 v[154:157], v154
	ds_read_b128 v[158:161], v158
	s_add_u32 s16, s16, 0x40000
	s_addc_u32 s17, s17, 0
	s_mov_b32 m0, s26
	v_lshl_add_u64 v[210:211], s[16:17], 0, v[136:137]
	ds_read_b128 v[162:165], v147 offset:32768
	ds_read_b128 v[166:169], v147 offset:33792
	ds_read_b128 v[170:173], v147 offset:34816
	ds_read_b128 v[174:177], v147 offset:35840
	ds_read_b128 v[194:197], v147 offset:36864
	ds_read_b128 v[198:201], v147 offset:37888
	ds_read_b128 v[202:205], v147 offset:38912
	ds_read_b128 v[206:209], v147 offset:39936
	global_load_lds_dwordx4 v[210:211], off
	v_lshl_add_u64 v[210:211], s[16:17], 0, v[134:135]
	s_mov_b32 m0, s27
	s_nop 0
	global_load_lds_dwordx4 v[210:211], off
	s_waitcnt lgkmcnt(8)
	s_barrier
	s_waitcnt lgkmcnt(0)
	s_setprio 1
	s_waitcnt lgkmcnt(0)
	v_mfma_f32_16x16x32_bf16 v[128:131], v[142:145], v[162:165], v[128:131]
	v_mfma_f32_16x16x32_bf16 v[124:127], v[154:157], v[162:165], v[124:127]
	v_mfma_f32_16x16x32_bf16 v[120:123], v[142:145], v[170:173], v[120:123]
	v_mfma_f32_16x16x32_bf16 v[112:115], v[154:157], v[170:173], v[112:115]
	v_mfma_f32_16x16x32_bf16 v[104:107], v[142:145], v[194:197], v[104:107]
	v_mfma_f32_16x16x32_bf16 v[96:99], v[154:157], v[194:197], v[96:99]
	v_mfma_f32_16x16x32_bf16 v[88:91], v[142:145], v[202:205], v[88:91]
	v_mfma_f32_16x16x32_bf16 v[80:83], v[154:157], v[202:205], v[80:83]
	v_mfma_f32_16x16x32_bf16 v[128:131], v[150:153], v[166:169], v[128:131]
	v_mfma_f32_16x16x32_bf16 v[124:127], v[158:161], v[166:169], v[124:127]
	v_mfma_f32_16x16x32_bf16 v[120:123], v[150:153], v[174:177], v[120:123]
	v_mfma_f32_16x16x32_bf16 v[112:115], v[158:161], v[174:177], v[112:115]
	v_mfma_f32_16x16x32_bf16 v[104:107], v[150:153], v[198:201], v[104:107]
	v_mfma_f32_16x16x32_bf16 v[96:99], v[158:161], v[198:201], v[96:99]
	v_mfma_f32_16x16x32_bf16 v[88:91], v[150:153], v[206:209], v[88:91]
	v_mfma_f32_16x16x32_bf16 v[80:83], v[158:161], v[206:209], v[80:83]
	s_setprio 0
	s_barrier
	v_or_b32_e32 v189, 0x1c000, v148
	v_add_u32_e32 v214, 0x1c400, v148
	s_mov_b32 m0, s28
	ds_read_b128 v[210:213], v189
	ds_read_b128 v[214:217], v214
	v_add_u32_e32 v189, 0x1c800, v148
	v_add_u32_e32 v222, 0x1cc00, v148
	v_lshl_add_u64 v[178:179], v[178:179], 0, s[82:83]
	ds_read_b128 v[218:221], v189
	ds_read_b128 v[222:225], v222
	global_load_lds_dwordx4 v[178:179], off
	v_lshl_add_u64 v[178:179], v[240:241], 0, s[82:83]
	s_mov_b32 m0, s29
	s_nop 0
	global_load_lds_dwordx4 v[178:179], off
	s_barrier
	s_waitcnt lgkmcnt(0)
	s_setprio 1
	s_waitcnt lgkmcnt(0)
	v_mfma_f32_16x16x32_bf16 v[116:119], v[210:213], v[162:165], v[116:119]
	v_mfma_f32_16x16x32_bf16 v[108:111], v[218:221], v[162:165], v[108:111]
	v_mfma_f32_16x16x32_bf16 v[100:103], v[210:213], v[170:173], v[100:103]
	v_mfma_f32_16x16x32_bf16 v[92:95], v[218:221], v[170:173], v[92:95]
	v_mfma_f32_16x16x32_bf16 v[84:87], v[210:213], v[194:197], v[84:87]
	v_mfma_f32_16x16x32_bf16 v[76:79], v[218:221], v[194:197], v[76:79]
	v_mfma_f32_16x16x32_bf16 v[72:75], v[210:213], v[202:205], v[72:75]
	v_mfma_f32_16x16x32_bf16 v[68:71], v[218:221], v[202:205], v[68:71]
	v_mfma_f32_16x16x32_bf16 v[116:119], v[214:217], v[166:169], v[116:119]
	v_mfma_f32_16x16x32_bf16 v[108:111], v[222:225], v[166:169], v[108:111]
	v_mfma_f32_16x16x32_bf16 v[100:103], v[214:217], v[174:177], v[100:103]
	v_mfma_f32_16x16x32_bf16 v[92:95], v[222:225], v[174:177], v[92:95]
	v_mfma_f32_16x16x32_bf16 v[84:87], v[214:217], v[198:201], v[84:87]
	v_mfma_f32_16x16x32_bf16 v[76:79], v[222:225], v[198:201], v[76:79]
	v_mfma_f32_16x16x32_bf16 v[72:75], v[214:217], v[206:209], v[72:75]
	v_mfma_f32_16x16x32_bf16 v[68:71], v[222:225], v[206:209], v[68:71]
	s_setprio 0
	s_mov_b32 m0, s30
	v_lshl_add_u64 v[178:179], v[242:243], 0, s[82:83]
	s_barrier
	ds_read_b128 v[162:165], v147 offset:49152
	ds_read_b128 v[166:169], v147 offset:50176
	ds_read_b128 v[170:173], v147 offset:51200
	ds_read_b128 v[174:177], v147 offset:52224
	ds_read_b128 v[194:197], v147 offset:53248
	ds_read_b128 v[198:201], v147 offset:54272
	ds_read_b128 v[202:205], v147 offset:55296
	ds_read_b128 v[206:209], v147 offset:56320
	global_load_lds_dwordx4 v[178:179], off
	v_lshl_add_u64 v[178:179], v[244:245], 0, s[82:83]
	s_mov_b32 m0, s31
	s_nop 0
	global_load_lds_dwordx4 v[178:179], off
	s_barrier
	s_waitcnt lgkmcnt(0)
	s_setprio 1
	s_waitcnt lgkmcnt(0)
	v_mfma_f32_16x16x32_bf16 v[64:67], v[142:145], v[162:165], v[64:67]
	v_mfma_f32_16x16x32_bf16 v[60:63], v[154:157], v[162:165], v[60:63]
	v_mfma_f32_16x16x32_bf16 v[56:59], v[142:145], v[170:173], v[56:59]
	v_mfma_f32_16x16x32_bf16 v[48:51], v[154:157], v[170:173], v[48:51]
	v_mfma_f32_16x16x32_bf16 v[40:43], v[142:145], v[194:197], v[40:43]
	v_mfma_f32_16x16x32_bf16 v[32:35], v[154:157], v[194:197], v[32:35]
	v_mfma_f32_16x16x32_bf16 v[24:27], v[142:145], v[202:205], v[24:27]
	v_mfma_f32_16x16x32_bf16 v[16:19], v[154:157], v[202:205], v[16:19]
	v_mfma_f32_16x16x32_bf16 v[64:67], v[150:153], v[166:169], v[64:67]
	v_mfma_f32_16x16x32_bf16 v[60:63], v[158:161], v[166:169], v[60:63]
	v_mfma_f32_16x16x32_bf16 v[56:59], v[150:153], v[174:177], v[56:59]
	v_mfma_f32_16x16x32_bf16 v[48:51], v[158:161], v[174:177], v[48:51]
	v_mfma_f32_16x16x32_bf16 v[40:43], v[150:153], v[198:201], v[40:43]
	v_mfma_f32_16x16x32_bf16 v[32:35], v[158:161], v[198:201], v[32:35]
	v_mfma_f32_16x16x32_bf16 v[24:27], v[150:153], v[206:209], v[24:27]
	v_mfma_f32_16x16x32_bf16 v[16:19], v[158:161], v[206:209], v[16:19]
	s_setprio 0
	s_barrier
	s_add_u32 s14, s14, 0x40080
	s_addc_u32 s15, s15, 0
	s_mov_b32 m0, s34
	v_lshl_add_u64 v[142:143], s[14:15], 0, v[2:3]
	global_load_lds_dwordx4 v[142:143], off
	v_lshl_add_u64 v[142:143], s[14:15], 0, v[132:133]
	s_mov_b32 m0, s35
	s_nop 0
	global_load_lds_dwordx4 v[142:143], off
	s_waitcnt vmcnt(6)
	s_barrier
	s_setprio 1
	v_mfma_f32_16x16x32_bf16 v[52:55], v[210:213], v[162:165], v[52:55]
	v_mfma_f32_16x16x32_bf16 v[44:47], v[218:221], v[162:165], v[44:47]
	v_mfma_f32_16x16x32_bf16 v[36:39], v[210:213], v[170:173], v[36:39]
	v_mfma_f32_16x16x32_bf16 v[28:31], v[218:221], v[170:173], v[28:31]
	v_mfma_f32_16x16x32_bf16 v[20:23], v[210:213], v[194:197], v[20:23]
	v_mfma_f32_16x16x32_bf16 v[12:15], v[218:221], v[194:197], v[12:15]
	v_mfma_f32_16x16x32_bf16 v[8:11], v[210:213], v[202:205], v[8:11]
	v_mfma_f32_16x16x32_bf16 v[4:7], v[218:221], v[202:205], v[4:7]
	v_mfma_f32_16x16x32_bf16 v[52:55], v[214:217], v[166:169], v[52:55]
	v_mfma_f32_16x16x32_bf16 v[44:47], v[222:225], v[166:169], v[44:47]
	v_mfma_f32_16x16x32_bf16 v[36:39], v[214:217], v[174:177], v[36:39]
	v_mfma_f32_16x16x32_bf16 v[28:31], v[222:225], v[174:177], v[28:31]
	v_mfma_f32_16x16x32_bf16 v[20:23], v[214:217], v[198:201], v[20:23]
	v_mfma_f32_16x16x32_bf16 v[12:15], v[222:225], v[198:201], v[12:15]
	v_mfma_f32_16x16x32_bf16 v[8:11], v[214:217], v[206:209], v[8:11]
	v_mfma_f32_16x16x32_bf16 v[4:7], v[222:225], v[206:209], v[4:7]
	s_setprio 0
	s_add_i32 s45, s45, 2
	s_add_u32 s12, s12, 0x100
	s_addc_u32 s13, s13, 0
	s_add_u32 s43, s43, 0x100
	s_addc_u32 s44, s44, 0
	s_cmp_gt_u32 s45, 13
	s_barrier
	s_cbranch_scc0 .LBB0_655
	v_readlane_b32 s12, v251, 12
	v_lshl_or_b32 v144, s39, 8, v149
	v_readlane_b32 s13, v251, 13
	v_lshl_add_u32 v152, s40, 8, v146
	v_ashrrev_i32_e32 v145, 31, v144
	v_mov_b64_e32 v[142:143], s[12:13]
	s_movk_i32 s5, 0x1200
	v_mad_i64_i32 v[150:151], s[12:13], v152, s5, v[142:143]
	v_lshlrev_b64 v[144:145], 1, v[144:145]
	v_lshl_add_u64 v[150:151], v[150:151], 0, v[144:145]
	v_cvt_pk_bf16_f32 v128, v128, v129
	v_cvt_pk_bf16_f32 v129, v130, v131
	v_cvt_pk_bf16_f32 v130, v124, v125
	v_cvt_pk_bf16_f32 v131, v126, v127
	global_store_dwordx4 v[150:151], v[128:131], off sc1
	v_cvt_pk_bf16_f32 v116, v116, v117
	v_cvt_pk_bf16_f32 v117, v118, v119
	v_cvt_pk_bf16_f32 v118, v108, v109
	v_or_b32_e32 v108, 16, v152
	v_mad_i64_i32 v[108:109], s[12:13], v108, s5, v[142:143]
	v_cvt_pk_bf16_f32 v119, v110, v111
	global_store_dwordx4 v[150:151], v[116:119], off offset:256 sc1
	s_and_b64 vcc, exec, s[2:3]
	s_mov_b32 s39, s4
	v_lshl_add_u64 v[116:117], v[108:109], 0, v[144:145]
	v_cvt_pk_bf16_f32 v108, v120, v121
	v_cvt_pk_bf16_f32 v109, v122, v123
	v_cvt_pk_bf16_f32 v110, v112, v113
	v_cvt_pk_bf16_f32 v111, v114, v115
	global_store_dwordx4 v[116:117], v[108:111], off sc1
	v_cvt_pk_bf16_f32 v100, v100, v101
	v_cvt_pk_bf16_f32 v101, v102, v103
	v_cvt_pk_bf16_f32 v102, v92, v93
	v_or_b32_e32 v92, 32, v152
	v_mad_i64_i32 v[92:93], s[12:13], v92, s5, v[142:143]
	v_cvt_pk_bf16_f32 v103, v94, v95
	global_store_dwordx4 v[116:117], v[100:103], off offset:256 sc1
	s_mov_b32 s40, s6
	s_mov_b64 s[14:15], s[10:11]
	v_lshl_add_u64 v[100:101], v[92:93], 0, v[144:145]
	v_cvt_pk_bf16_f32 v92, v104, v105
	v_cvt_pk_bf16_f32 v93, v106, v107
	v_cvt_pk_bf16_f32 v94, v96, v97
	v_cvt_pk_bf16_f32 v95, v98, v99
	global_store_dwordx4 v[100:101], v[92:95], off sc1
	v_cvt_pk_bf16_f32 v84, v84, v85
	v_cvt_pk_bf16_f32 v85, v86, v87
	v_cvt_pk_bf16_f32 v86, v76, v77
	v_or_b32_e32 v76, 48, v152
	v_mad_i64_i32 v[76:77], s[12:13], v76, s5, v[142:143]
	v_cvt_pk_bf16_f32 v87, v78, v79
	global_store_dwordx4 v[100:101], v[84:87], off offset:256 sc1
	s_nop 1
	v_lshl_add_u64 v[84:85], v[76:77], 0, v[144:145]
	v_cvt_pk_bf16_f32 v76, v88, v89
	v_cvt_pk_bf16_f32 v77, v90, v91
	v_cvt_pk_bf16_f32 v78, v80, v81
	v_cvt_pk_bf16_f32 v79, v82, v83
	global_store_dwordx4 v[84:85], v[76:79], off sc1
	v_cvt_pk_bf16_f32 v72, v72, v73
	v_cvt_pk_bf16_f32 v73, v74, v75
	v_cvt_pk_bf16_f32 v74, v68, v69
	v_add_u32_e32 v68, 0x80, v152
	v_mad_i64_i32 v[68:69], s[12:13], v68, s5, v[142:143]
	v_lshl_add_u64 v[68:69], v[68:69], 0, v[144:145]
	v_cvt_pk_bf16_f32 v75, v70, v71
	global_store_dwordx4 v[84:85], v[72:75], off offset:256 sc1
	v_cvt_pk_bf16_f32 v64, v64, v65
	v_cvt_pk_bf16_f32 v65, v66, v67
	v_cvt_pk_bf16_f32 v66, v60, v61
	v_cvt_pk_bf16_f32 v67, v62, v63
	global_store_dwordx4 v[68:69], v[64:67], off sc1
	v_cvt_pk_bf16_f32 v52, v52, v53
	v_cvt_pk_bf16_f32 v53, v54, v55
	v_cvt_pk_bf16_f32 v54, v44, v45
	v_add_u32_e32 v44, 0x90, v152
	v_mad_i64_i32 v[44:45], s[12:13], v44, s5, v[142:143]
	v_cvt_pk_bf16_f32 v55, v46, v47
	global_store_dwordx4 v[68:69], v[52:55], off offset:256 sc1
	s_nop 1
	v_lshl_add_u64 v[52:53], v[44:45], 0, v[144:145]
	v_cvt_pk_bf16_f32 v44, v56, v57
	v_cvt_pk_bf16_f32 v45, v58, v59
	v_cvt_pk_bf16_f32 v46, v48, v49
	v_cvt_pk_bf16_f32 v47, v50, v51
	global_store_dwordx4 v[52:53], v[44:47], off sc1
	v_cvt_pk_bf16_f32 v36, v36, v37
	v_cvt_pk_bf16_f32 v37, v38, v39
	v_cvt_pk_bf16_f32 v38, v28, v29
	v_add_u32_e32 v28, 0xa0, v152
	v_mad_i64_i32 v[28:29], s[12:13], v28, s5, v[142:143]
	v_cvt_pk_bf16_f32 v39, v30, v31
	global_store_dwordx4 v[52:53], v[36:39], off offset:256 sc1
	s_nop 1
	v_lshl_add_u64 v[36:37], v[28:29], 0, v[144:145]
	v_cvt_pk_bf16_f32 v28, v40, v41
	v_cvt_pk_bf16_f32 v29, v42, v43
	v_cvt_pk_bf16_f32 v30, v32, v33
	v_cvt_pk_bf16_f32 v31, v34, v35
	global_store_dwordx4 v[36:37], v[28:31], off sc1
	v_cvt_pk_bf16_f32 v20, v20, v21
	v_cvt_pk_bf16_f32 v21, v22, v23
	v_cvt_pk_bf16_f32 v22, v12, v13
	v_add_u32_e32 v12, 0xb0, v152
	v_mad_i64_i32 v[12:13], s[12:13], v12, s5, v[142:143]
	v_cvt_pk_bf16_f32 v23, v14, v15
	global_store_dwordx4 v[36:37], v[20:23], off offset:256 sc1
	s_mov_b64 s[12:13], s[8:9]
	s_nop 0
	v_lshl_add_u64 v[20:21], v[12:13], 0, v[144:145]
	v_cvt_pk_bf16_f32 v12, v24, v25
	v_cvt_pk_bf16_f32 v13, v26, v27
	v_cvt_pk_bf16_f32 v14, v16, v17
	v_cvt_pk_bf16_f32 v15, v18, v19
	global_store_dwordx4 v[20:21], v[12:15], off sc1
	v_cvt_pk_bf16_f32 v8, v8, v9
	v_cvt_pk_bf16_f32 v9, v10, v11
	v_cvt_pk_bf16_f32 v10, v4, v5
	v_cvt_pk_bf16_f32 v11, v6, v7
	global_store_dwordx4 v[20:21], v[8:11], off offset:256 sc1
	s_cbranch_vccz .LBB0_652
	s_waitcnt vmcnt(0)
	s_cmpk_gt_u32 s0, 0xff
	s_cbranch_scc1 .LBB0_659
	s_barrier

.LBB0_1326:
	s_waitcnt lgkmcnt(0)
	s_nop 0
	v_readfirstlane_b32 s2, v4
	v_readfirstlane_b32 s3, v2
	v_readlane_b32 s4, v254, 1
	s_lshl_b32 s0, s0, 8
	s_add_u32 s10, s38, s0
	s_addc_u32 s11, s39, 0
	s_add_u32 s12, s10, 0x1400
	s_addc_u32 s13, s11, 0
	s_add_i32 s5, s4, 1
	v_writelane_b32 v254, s5, 1
	s_mul_i32 s6, s5, s2
	s_mul_i32 s7, s5, s3
	v_mov_b32_e32 v5, 0
	global_atomic_add v6, v5, v228, s[12:13] sc0
	s_add_u32 s12, s10, 0x2400
	s_addc_u32 s13, s11, 0
	s_waitcnt vmcnt(0)
	v_readfirstlane_b32 s8, v6
	s_add_i32 s8, s8, 1
	s_cmp_eq_u32 s8, s6
	s_cbranch_scc1 .Lxb_leader
	s_mov_b32 s9, 0
.Lxb_wait_local:
	s_sleep 1
	global_load_dword v6, v5, s[12:13] sc1
	s_add_i32 s9, s9, 1
	s_waitcnt vmcnt(0)
	v_readfirstlane_b32 s8, v6
	s_cmp_lg_u32 s8, s4
	s_cbranch_scc1 .Lxb_acquire
	s_cmp_lt_u32 s9, 0x1000000
	s_cbranch_scc1 .Lxb_wait_local
	s_branch .Lxb_acquire
.Lxb_leader:
	buffer_wbl2 sc1
	s_waitcnt vmcnt(0)
	s_add_u32 s10, s38, 0x3400
	s_addc_u32 s11, s39, 0
	global_atomic_add v5, v228, s[10:11]
	s_mov_b32 s9, 0
.Lxb_wait_top:
	global_load_dword v6, v5, s[10:11] sc1
	s_add_i32 s9, s9, 1
	s_waitcnt vmcnt(0)
	v_readfirstlane_b32 s8, v6
	s_cmp_ge_u32 s8, s7
	s_cbranch_scc1 .Lxb_release
	s_sleep 1
	s_cmp_lt_u32 s9, 0x1000000
	s_cbranch_scc1 .Lxb_wait_top
.Lxb_release:
	global_atomic_add v5, v228, s[12:13]
.Lxb_acquire:
	buffer_inv sc1
	s_waitcnt vmcnt(0)
	s_branch .LBB0_10

	.amdhsa_kernel _Z4mega6Params
		.amdhsa_group_segment_fixed_size 141328
		.amdhsa_private_segment_fixed_size 0
		.amdhsa_kernarg_size 520
		.amdhsa_user_sgpr_count 2
		.amdhsa_user_sgpr_dispatch_ptr 0
		.amdhsa_user_sgpr_queue_ptr 0
		.amdhsa_user_sgpr_kernarg_segment_ptr 1
		.amdhsa_user_sgpr_dispatch_id 0
		.amdhsa_user_sgpr_kernarg_preload_length 0
		.amdhsa_user_sgpr_kernarg_preload_offset 0
		.amdhsa_user_sgpr_private_segment_size 0
		.amdhsa_uses_dynamic_stack 0
		.amdhsa_enable_private_segment 0
		.amdhsa_system_sgpr_workgroup_id_x 1
		.amdhsa_system_sgpr_workgroup_id_y 0
		.amdhsa_system_sgpr_workgroup_id_z 0
		.amdhsa_system_sgpr_workgroup_info 0
		.amdhsa_system_vgpr_workitem_id 0
		.amdhsa_next_free_vgpr 256
		.amdhsa_next_free_sgpr 102
		.amdhsa_accum_offset 256
		.amdhsa_reserve_vcc 1
		.amdhsa_float_round_mode_32 0
		.amdhsa_float_round_mode_16_64 0
		.amdhsa_float_denorm_mode_32 3
		.amdhsa_float_denorm_mode_16_64 3
		.amdhsa_dx10_clamp 1
		.amdhsa_ieee_mode 1
		.amdhsa_fp16_overflow 0
		.amdhsa_tg_split 0
		.amdhsa_exception_fp_ieee_invalid_op 0
		.amdhsa_exception_fp_denorm_src 0
		.amdhsa_exception_fp_ieee_div_zero 0
		.amdhsa_exception_fp_ieee_overflow 0
		.amdhsa_exception_fp_ieee_underflow 0
		.amdhsa_exception_fp_ieee_inexact 0
		.amdhsa_exception_int_div_zero 0
	.end_amdhsa_kernel

amdhsa.kernels:
  - .agpr_count:     0
    .args:
      - .offset:         0
        .size:           264
        .value_kind:     by_value
      - .offset:         264
        .size:           4
        .value_kind:     hidden_block_count_x
      - .offset:         268
        .size:           4
        .value_kind:     hidden_block_count_y
      - .offset:         272
        .size:           4
        .value_kind:     hidden_block_count_z
      - .offset:         276
        .size:           2
        .value_kind:     hidden_group_size_x
      - .offset:         278
        .size:           2
        .value_kind:     hidden_group_size_y
      - .offset:         280
        .size:           2
        .value_kind:     hidden_group_size_z
      - .offset:         282
        .size:           2
        .value_kind:     hidden_remainder_x
      - .offset:         284
        .size:           2
        .value_kind:     hidden_remainder_y
      - .offset:         286
        .size:           2
        .value_kind:     hidden_remainder_z
      - .offset:         304
        .size:           8
        .value_kind:     hidden_global_offset_x
      - .offset:         312
        .size:           8
        .value_kind:     hidden_global_offset_y
      - .offset:         320
        .size:           8
        .value_kind:     hidden_global_offset_z
      - .offset:         328
        .size:           2
        .value_kind:     hidden_grid_dims
    .group_segment_fixed_size: 141328
    .kernarg_segment_align: 8
    .kernarg_segment_size: 520
    .language:       OpenCL C
    .language_version:
      - 2
      - 0
    .max_flat_workgroup_size: 512
    .name:           _Z4mega6Params
    .private_segment_fixed_size: 0
    .sgpr_count:     108
    .sgpr_spill_count: 250
    .symbol:         _Z4mega6Params.kd
    .uniform_work_group_size: 1
    .uses_dynamic_stack: false
    .vgpr_count:     256
    .vgpr_spill_count: 0
    .wavefront_size: 64
